# scan waves: counted lgkmcnt waits per consumer instead of one lgkmcnt(0) per step (gen_scan4.py) on top of v181
# speedup vs baseline: 1.0135x; 1.0135x over previous
.LBB0_390:
	s_and_b32 s3, s2, 1
	s_mul_i32 s8, s3, 0x5000
	v_add_u32_e32 v2, s8, v136
	s_mul_i32 s8, s2, 0xab
	s_bfe_u32 s8, s8, 0x70009
	s_mul_i32 s8, s8, 3
	s_sub_i32 s8, s2, s8
	s_and_b32 s8, s8, 0xff
	s_mulk_i32 s8, 0x1100
	v_add_u32_e32 v3, s8, v137
	v_lshl_add_u32 v1, s3, 12, v137
	ds_read_b128 v[176:179], v2 offset:4096
	ds_read_b128 v[180:183], v2 offset:4112
	ds_read_b128 v[200:203], v2 offset:12288
	ds_read_b128 v[204:207], v2 offset:12304
	ds_read_b64 v[216:217], v3 offset:40960
	ds_read_b128 v[184:187], v2 offset:0
	ds_read_b128 v[188:191], v2 offset:16
	ds_read_b128 v[192:195], v2 offset:8192
	ds_read_b128 v[196:199], v2 offset:8208
	s_waitcnt lgkmcnt(8)
	v_pk_mul_f32 v[164:165], v[72:73], v[176:177]
	v_pk_mul_f32 v[166:167], v[80:81], v[176:177]
	ds_read_b128 v[208:211], v2 offset:16384
	v_pk_fma_f32 v[164:165], v[74:75], v[178:179], v[164:165]
	v_pk_fma_f32 v[166:167], v[82:83], v[178:179], v[166:167]
	ds_read_b128 v[212:215], v2 offset:16400
	s_waitcnt lgkmcnt(9)
	v_pk_fma_f32 v[164:165], v[76:77], v[180:181], v[164:165]
	v_pk_fma_f32 v[166:167], v[84:85], v[180:181], v[166:167]
	ds_read_b128 v[4:7], v2 offset:4352
	v_pk_fma_f32 v[164:165], v[78:79], v[182:183], v[164:165]
	v_pk_fma_f32 v[166:167], v[86:87], v[182:183], v[166:167]
	ds_read_b128 v[8:11], v2 offset:4368
	s_waitcnt lgkmcnt(8)
	v_pk_mul_f32 v[218:219], v[216:217], v[200:201] op_sel_hi:[0,1]
	v_pk_mul_f32 v[226:227], v[216:217], v[200:201] op_sel:[1,0]
	ds_read_b128 v[40:43], v2 offset:12544
	v_pk_mul_f32 v[220:221], v[216:217], v[202:203] op_sel_hi:[0,1]
	v_pk_mul_f32 v[228:229], v[216:217], v[202:203] op_sel:[1,0]
	ds_read_b128 v[44:47], v2 offset:12560
	v_pk_mul_f32 v[222:223], v[216:217], v[204:205] op_sel_hi:[0,1]
	v_pk_mul_f32 v[230:231], v[216:217], v[204:205] op_sel:[1,0]
	ds_read_b64 v[26:27], v3 offset:41216
	v_pk_mul_f32 v[224:225], v[216:217], v[206:207] op_sel_hi:[0,1]
	v_pk_mul_f32 v[234:235], v[216:217], v[206:207] op_sel:[1,0]
	ds_read_b128 v[12:15], v2 offset:256
	v_add_f32_e32 v172, v164, v165
	v_add_f32_e32 v174, v166, v167
	ds_read_b128 v[28:31], v2 offset:272
	s_waitcnt lgkmcnt(12)
	v_pk_fma_f32 v[218:219], v[72:73], v[184:185], v[218:219]
	v_pk_fma_f32 v[226:227], v[80:81], v[184:185], v[226:227]
	ds_read_b128 v[32:35], v2 offset:8448
	v_pk_fma_f32 v[220:221], v[74:75], v[186:187], v[220:221]
	v_pk_fma_f32 v[228:229], v[82:83], v[186:187], v[228:229]
	ds_read_b128 v[36:39], v2 offset:8464
	v_add_f32_dpp v172, v172, v172 quad_perm:[1,0,3,2] row_mask:0xf bank_mask:0xf bound_ctrl:1
	v_add_f32_dpp v174, v174, v174 quad_perm:[1,0,3,2] row_mask:0xf bank_mask:0xf bound_ctrl:1
	s_waitcnt lgkmcnt(13)
	v_pk_fma_f32 v[222:223], v[76:77], v[188:189], v[222:223]
	v_pk_fma_f32 v[230:231], v[84:85], v[188:189], v[230:231]
	v_pk_fma_f32 v[224:225], v[78:79], v[190:191], v[224:225]
	v_pk_fma_f32 v[234:235], v[86:87], v[190:191], v[234:235]
	v_add_f32_dpp v172, v172, v172 quad_perm:[2,3,0,1] row_mask:0xf bank_mask:0xf bound_ctrl:1
	v_add_f32_dpp v174, v174, v174 quad_perm:[2,3,0,1] row_mask:0xf bank_mask:0xf bound_ctrl:1
	s_nop 0
	v_add_f32_dpp v172, v172, v172 row_half_mirror row_mask:0xf bank_mask:0xf bound_ctrl:1
	v_add_f32_dpp v174, v174, v174 row_half_mirror row_mask:0xf bank_mask:0xf bound_ctrl:1
	s_waitcnt lgkmcnt(12)
	v_pk_fma_f32 v[72:73], v[192:193], v[172:173], v[218:219] op_sel_hi:[1,0,1]
	v_pk_fma_f32 v[80:81], v[192:193], v[174:175], v[226:227] op_sel_hi:[1,0,1]
	v_pk_fma_f32 v[74:75], v[194:195], v[172:173], v[220:221] op_sel_hi:[1,0,1]
	v_pk_fma_f32 v[82:83], v[194:195], v[174:175], v[228:229] op_sel_hi:[1,0,1]
	s_waitcnt lgkmcnt(11)
	v_pk_fma_f32 v[76:77], v[196:197], v[172:173], v[222:223] op_sel_hi:[1,0,1]
	v_pk_fma_f32 v[84:85], v[196:197], v[174:175], v[230:231] op_sel_hi:[1,0,1]
	v_pk_fma_f32 v[78:79], v[198:199], v[172:173], v[224:225] op_sel_hi:[1,0,1]
	v_pk_fma_f32 v[86:87], v[198:199], v[174:175], v[234:235] op_sel_hi:[1,0,1]
	s_waitcnt lgkmcnt(8)
	v_pk_mul_f32 v[164:165], v[72:73], v[4:5]
	v_pk_mul_f32 v[166:167], v[80:81], v[4:5]
	ds_read_b128 v[48:51], v2 offset:16640
	v_pk_mul_f32 v[168:169], v[72:73], v[208:209]
	v_pk_mul_f32 v[170:171], v[80:81], v[208:209]
	ds_read_b128 v[52:55], v2 offset:16656
	v_pk_fma_f32 v[164:165], v[74:75], v[6:7], v[164:165]
	v_pk_fma_f32 v[166:167], v[82:83], v[6:7], v[166:167]
	ds_read_b128 v[176:179], v2 offset:4608
	v_pk_fma_f32 v[168:169], v[74:75], v[210:211], v[168:169]
	v_pk_fma_f32 v[170:171], v[82:83], v[210:211], v[170:171]
	ds_read_b128 v[180:183], v2 offset:4624
	s_waitcnt lgkmcnt(11)
	v_pk_fma_f32 v[164:165], v[76:77], v[8:9], v[164:165]
	v_pk_fma_f32 v[166:167], v[84:85], v[8:9], v[166:167]
	ds_read_b128 v[200:203], v2 offset:12800
	v_pk_fma_f32 v[168:169], v[76:77], v[212:213], v[168:169]
	v_pk_fma_f32 v[170:171], v[84:85], v[212:213], v[170:171]
	ds_read_b128 v[204:207], v2 offset:12816
	v_pk_fma_f32 v[164:165], v[78:79], v[10:11], v[164:165]
	v_pk_fma_f32 v[166:167], v[86:87], v[10:11], v[166:167]
	ds_read_b64 v[216:217], v3 offset:41472
	v_pk_fma_f32 v[168:169], v[78:79], v[214:215], v[168:169]
	v_pk_fma_f32 v[170:171], v[86:87], v[214:215], v[170:171]
	ds_read_b128 v[184:187], v2 offset:512
	s_waitcnt lgkmcnt(12)
	v_pk_mul_f32 v[218:219], v[26:27], v[40:41] op_sel_hi:[0,1]
	v_pk_mul_f32 v[226:227], v[26:27], v[40:41] op_sel:[1,0]
	ds_read_b128 v[188:191], v2 offset:528
	v_pk_mul_f32 v[220:221], v[26:27], v[42:43] op_sel_hi:[0,1]
	v_pk_mul_f32 v[228:229], v[26:27], v[42:43] op_sel:[1,0]
	ds_read_b128 v[192:195], v2 offset:8704
	v_pk_mul_f32 v[222:223], v[26:27], v[44:45] op_sel_hi:[0,1]
	v_pk_mul_f32 v[230:231], v[26:27], v[44:45] op_sel:[1,0]
	ds_read_b128 v[196:199], v2 offset:8720
	v_pk_mul_f32 v[224:225], v[26:27], v[46:47] op_sel_hi:[0,1]
	v_pk_mul_f32 v[234:235], v[26:27], v[46:47] op_sel:[1,0]
	v_add_f32_e32 v172, v164, v165
	v_add_f32_e32 v174, v166, v167
	v_add_f32_e32 v160, v168, v169
	v_add_f32_e32 v161, v170, v171
	s_waitcnt lgkmcnt(14)
	v_pk_fma_f32 v[218:219], v[72:73], v[12:13], v[218:219]
	v_pk_fma_f32 v[226:227], v[80:81], v[12:13], v[226:227]
	v_pk_fma_f32 v[220:221], v[74:75], v[14:15], v[220:221]
	v_pk_fma_f32 v[228:229], v[82:83], v[14:15], v[228:229]
	v_add_f32_dpp v172, v172, v172 quad_perm:[1,0,3,2] row_mask:0xf bank_mask:0xf bound_ctrl:1
	v_add_f32_dpp v174, v174, v174 quad_perm:[1,0,3,2] row_mask:0xf bank_mask:0xf bound_ctrl:1
	v_add_f32_dpp v160, v160, v160 quad_perm:[1,0,3,2] row_mask:0xf bank_mask:0xf bound_ctrl:1
	v_add_f32_dpp v161, v161, v161 quad_perm:[1,0,3,2] row_mask:0xf bank_mask:0xf bound_ctrl:1
	s_waitcnt lgkmcnt(13)
	v_pk_fma_f32 v[222:223], v[76:77], v[28:29], v[222:223]
	v_pk_fma_f32 v[230:231], v[84:85], v[28:29], v[230:231]
	v_pk_fma_f32 v[224:225], v[78:79], v[30:31], v[224:225]
	v_pk_fma_f32 v[234:235], v[86:87], v[30:31], v[234:235]
	v_add_f32_dpp v172, v172, v172 quad_perm:[2,3,0,1] row_mask:0xf bank_mask:0xf bound_ctrl:1
	v_add_f32_dpp v174, v174, v174 quad_perm:[2,3,0,1] row_mask:0xf bank_mask:0xf bound_ctrl:1
	v_add_f32_dpp v160, v160, v160 quad_perm:[2,3,0,1] row_mask:0xf bank_mask:0xf bound_ctrl:1
	v_add_f32_dpp v161, v161, v161 quad_perm:[2,3,0,1] row_mask:0xf bank_mask:0xf bound_ctrl:1
	v_add_f32_dpp v172, v172, v172 row_half_mirror row_mask:0xf bank_mask:0xf bound_ctrl:1
	v_add_f32_dpp v174, v174, v174 row_half_mirror row_mask:0xf bank_mask:0xf bound_ctrl:1
	v_add_f32_dpp v160, v160, v160 row_half_mirror row_mask:0xf bank_mask:0xf bound_ctrl:1
	v_add_f32_dpp v161, v161, v161 row_half_mirror row_mask:0xf bank_mask:0xf bound_ctrl:1
	s_waitcnt lgkmcnt(12)
	v_pk_fma_f32 v[72:73], v[32:33], v[172:173], v[218:219] op_sel_hi:[1,0,1]
	v_pk_fma_f32 v[80:81], v[32:33], v[174:175], v[226:227] op_sel_hi:[1,0,1]
	v_pk_fma_f32 v[74:75], v[34:35], v[172:173], v[220:221] op_sel_hi:[1,0,1]
	v_pk_fma_f32 v[82:83], v[34:35], v[174:175], v[228:229] op_sel_hi:[1,0,1]
	s_waitcnt lgkmcnt(11)
	v_pk_fma_f32 v[76:77], v[36:37], v[172:173], v[222:223] op_sel_hi:[1,0,1]
	v_pk_fma_f32 v[84:85], v[36:37], v[174:175], v[230:231] op_sel_hi:[1,0,1]
	v_pk_fma_f32 v[78:79], v[38:39], v[172:173], v[224:225] op_sel_hi:[1,0,1]
	v_pk_fma_f32 v[86:87], v[38:39], v[174:175], v[234:235] op_sel_hi:[1,0,1]
	ds_write_b64 v1, v[160:161] offset:54016
	s_waitcnt lgkmcnt(9)
	v_pk_mul_f32 v[164:165], v[72:73], v[176:177]
	v_pk_mul_f32 v[166:167], v[80:81], v[176:177]
	ds_read_b128 v[208:211], v2 offset:16896
	v_pk_mul_f32 v[168:169], v[72:73], v[48:49]
	v_pk_mul_f32 v[170:171], v[80:81], v[48:49]
	ds_read_b128 v[212:215], v2 offset:16912
	v_pk_fma_f32 v[164:165], v[74:75], v[178:179], v[164:165]
	v_pk_fma_f32 v[166:167], v[82:83], v[178:179], v[166:167]
	ds_read_b128 v[4:7], v2 offset:4864
	v_pk_fma_f32 v[168:169], v[74:75], v[50:51], v[168:169]
	v_pk_fma_f32 v[170:171], v[82:83], v[50:51], v[170:171]
	ds_read_b128 v[8:11], v2 offset:4880
	s_waitcnt lgkmcnt(12)
	v_pk_fma_f32 v[164:165], v[76:77], v[180:181], v[164:165]
	v_pk_fma_f32 v[166:167], v[84:85], v[180:181], v[166:167]
	ds_read_b128 v[40:43], v2 offset:13056
	v_pk_fma_f32 v[168:169], v[76:77], v[52:53], v[168:169]
	v_pk_fma_f32 v[170:171], v[84:85], v[52:53], v[170:171]
	ds_read_b128 v[44:47], v2 offset:13072
	v_pk_fma_f32 v[164:165], v[78:79], v[182:183], v[164:165]
	v_pk_fma_f32 v[166:167], v[86:87], v[182:183], v[166:167]
	ds_read_b64 v[26:27], v3 offset:41728
	v_pk_fma_f32 v[168:169], v[78:79], v[54:55], v[168:169]
	v_pk_fma_f32 v[170:171], v[86:87], v[54:55], v[170:171]
	ds_read_b128 v[12:15], v2 offset:768
	s_waitcnt lgkmcnt(13)
	v_pk_mul_f32 v[218:219], v[216:217], v[200:201] op_sel_hi:[0,1]
	v_pk_mul_f32 v[226:227], v[216:217], v[200:201] op_sel:[1,0]
	ds_read_b128 v[28:31], v2 offset:784
	v_pk_mul_f32 v[220:221], v[216:217], v[202:203] op_sel_hi:[0,1]
	v_pk_mul_f32 v[228:229], v[216:217], v[202:203] op_sel:[1,0]
	ds_read_b128 v[32:35], v2 offset:8960
	v_pk_mul_f32 v[222:223], v[216:217], v[204:205] op_sel_hi:[0,1]
	v_pk_mul_f32 v[230:231], v[216:217], v[204:205] op_sel:[1,0]
	ds_read_b128 v[36:39], v2 offset:8976
	v_pk_mul_f32 v[224:225], v[216:217], v[206:207] op_sel_hi:[0,1]
	v_pk_mul_f32 v[234:235], v[216:217], v[206:207] op_sel:[1,0]
	v_add_f32_e32 v172, v164, v165
	v_add_f32_e32 v174, v166, v167
	v_add_f32_e32 v160, v168, v169
	v_add_f32_e32 v161, v170, v171
	s_waitcnt lgkmcnt(15)
	v_pk_fma_f32 v[218:219], v[72:73], v[184:185], v[218:219]
	v_pk_fma_f32 v[226:227], v[80:81], v[184:185], v[226:227]
	v_pk_fma_f32 v[220:221], v[74:75], v[186:187], v[220:221]
	v_pk_fma_f32 v[228:229], v[82:83], v[186:187], v[228:229]
	v_add_f32_dpp v172, v172, v172 quad_perm:[1,0,3,2] row_mask:0xf bank_mask:0xf bound_ctrl:1
	v_add_f32_dpp v174, v174, v174 quad_perm:[1,0,3,2] row_mask:0xf bank_mask:0xf bound_ctrl:1
	v_add_f32_dpp v160, v160, v160 quad_perm:[1,0,3,2] row_mask:0xf bank_mask:0xf bound_ctrl:1
	v_add_f32_dpp v161, v161, v161 quad_perm:[1,0,3,2] row_mask:0xf bank_mask:0xf bound_ctrl:1
	s_waitcnt lgkmcnt(14)
	v_pk_fma_f32 v[222:223], v[76:77], v[188:189], v[222:223]
	v_pk_fma_f32 v[230:231], v[84:85], v[188:189], v[230:231]
	v_pk_fma_f32 v[224:225], v[78:79], v[190:191], v[224:225]
	v_pk_fma_f32 v[234:235], v[86:87], v[190:191], v[234:235]
	v_add_f32_dpp v172, v172, v172 quad_perm:[2,3,0,1] row_mask:0xf bank_mask:0xf bound_ctrl:1
	v_add_f32_dpp v174, v174, v174 quad_perm:[2,3,0,1] row_mask:0xf bank_mask:0xf bound_ctrl:1
	v_add_f32_dpp v160, v160, v160 quad_perm:[2,3,0,1] row_mask:0xf bank_mask:0xf bound_ctrl:1
	v_add_f32_dpp v161, v161, v161 quad_perm:[2,3,0,1] row_mask:0xf bank_mask:0xf bound_ctrl:1
	v_add_f32_dpp v172, v172, v172 row_half_mirror row_mask:0xf bank_mask:0xf bound_ctrl:1
	v_add_f32_dpp v174, v174, v174 row_half_mirror row_mask:0xf bank_mask:0xf bound_ctrl:1
	v_add_f32_dpp v160, v160, v160 row_half_mirror row_mask:0xf bank_mask:0xf bound_ctrl:1
	v_add_f32_dpp v161, v161, v161 row_half_mirror row_mask:0xf bank_mask:0xf bound_ctrl:1
	s_waitcnt lgkmcnt(13)
	v_pk_fma_f32 v[72:73], v[192:193], v[172:173], v[218:219] op_sel_hi:[1,0,1]
	v_pk_fma_f32 v[80:81], v[192:193], v[174:175], v[226:227] op_sel_hi:[1,0,1]
	v_pk_fma_f32 v[74:75], v[194:195], v[172:173], v[220:221] op_sel_hi:[1,0,1]
	v_pk_fma_f32 v[82:83], v[194:195], v[174:175], v[228:229] op_sel_hi:[1,0,1]
	s_waitcnt lgkmcnt(12)
	v_pk_fma_f32 v[76:77], v[196:197], v[172:173], v[222:223] op_sel_hi:[1,0,1]
	v_pk_fma_f32 v[84:85], v[196:197], v[174:175], v[230:231] op_sel_hi:[1,0,1]
	v_pk_fma_f32 v[78:79], v[198:199], v[172:173], v[224:225] op_sel_hi:[1,0,1]
	v_pk_fma_f32 v[86:87], v[198:199], v[174:175], v[234:235] op_sel_hi:[1,0,1]
	ds_write_b64 v1, v[160:161] offset:54272
	s_waitcnt lgkmcnt(9)
	v_pk_mul_f32 v[164:165], v[72:73], v[4:5]
	v_pk_mul_f32 v[166:167], v[80:81], v[4:5]
	ds_read_b128 v[48:51], v2 offset:17152
	v_pk_mul_f32 v[168:169], v[72:73], v[208:209]
	v_pk_mul_f32 v[170:171], v[80:81], v[208:209]
	ds_read_b128 v[52:55], v2 offset:17168
	v_pk_fma_f32 v[164:165], v[74:75], v[6:7], v[164:165]
	v_pk_fma_f32 v[166:167], v[82:83], v[6:7], v[166:167]
	ds_read_b128 v[176:179], v2 offset:5120
	v_pk_fma_f32 v[168:169], v[74:75], v[210:211], v[168:169]
	v_pk_fma_f32 v[170:171], v[82:83], v[210:211], v[170:171]
	ds_read_b128 v[180:183], v2 offset:5136
	s_waitcnt lgkmcnt(12)
	v_pk_fma_f32 v[164:165], v[76:77], v[8:9], v[164:165]
	v_pk_fma_f32 v[166:167], v[84:85], v[8:9], v[166:167]
	ds_read_b128 v[200:203], v2 offset:13312
	v_pk_fma_f32 v[168:169], v[76:77], v[212:213], v[168:169]
	v_pk_fma_f32 v[170:171], v[84:85], v[212:213], v[170:171]
	ds_read_b128 v[204:207], v2 offset:13328
	v_pk_fma_f32 v[164:165], v[78:79], v[10:11], v[164:165]
	v_pk_fma_f32 v[166:167], v[86:87], v[10:11], v[166:167]
	ds_read_b64 v[216:217], v3 offset:41984
	v_pk_fma_f32 v[168:169], v[78:79], v[214:215], v[168:169]
	v_pk_fma_f32 v[170:171], v[86:87], v[214:215], v[170:171]
	ds_read_b128 v[184:187], v2 offset:1024
	s_waitcnt lgkmcnt(13)
	v_pk_mul_f32 v[218:219], v[26:27], v[40:41] op_sel_hi:[0,1]
	v_pk_mul_f32 v[226:227], v[26:27], v[40:41] op_sel:[1,0]
	ds_read_b128 v[188:191], v2 offset:1040
	v_pk_mul_f32 v[220:221], v[26:27], v[42:43] op_sel_hi:[0,1]
	v_pk_mul_f32 v[228:229], v[26:27], v[42:43] op_sel:[1,0]
	ds_read_b128 v[192:195], v2 offset:9216
	v_pk_mul_f32 v[222:223], v[26:27], v[44:45] op_sel_hi:[0,1]
	v_pk_mul_f32 v[230:231], v[26:27], v[44:45] op_sel:[1,0]
	ds_read_b128 v[196:199], v2 offset:9232
	v_pk_mul_f32 v[224:225], v[26:27], v[46:47] op_sel_hi:[0,1]
	v_pk_mul_f32 v[234:235], v[26:27], v[46:47] op_sel:[1,0]
	v_add_f32_e32 v172, v164, v165
	v_add_f32_e32 v174, v166, v167
	v_add_f32_e32 v160, v168, v169
	v_add_f32_e32 v161, v170, v171
	s_waitcnt lgkmcnt(15)
	v_pk_fma_f32 v[218:219], v[72:73], v[12:13], v[218:219]
	v_pk_fma_f32 v[226:227], v[80:81], v[12:13], v[226:227]
	v_pk_fma_f32 v[220:221], v[74:75], v[14:15], v[220:221]
	v_pk_fma_f32 v[228:229], v[82:83], v[14:15], v[228:229]
	v_add_f32_dpp v172, v172, v172 quad_perm:[1,0,3,2] row_mask:0xf bank_mask:0xf bound_ctrl:1
	v_add_f32_dpp v174, v174, v174 quad_perm:[1,0,3,2] row_mask:0xf bank_mask:0xf bound_ctrl:1
	v_add_f32_dpp v160, v160, v160 quad_perm:[1,0,3,2] row_mask:0xf bank_mask:0xf bound_ctrl:1
	v_add_f32_dpp v161, v161, v161 quad_perm:[1,0,3,2] row_mask:0xf bank_mask:0xf bound_ctrl:1
	s_waitcnt lgkmcnt(14)
	v_pk_fma_f32 v[222:223], v[76:77], v[28:29], v[222:223]
	v_pk_fma_f32 v[230:231], v[84:85], v[28:29], v[230:231]
	v_pk_fma_f32 v[224:225], v[78:79], v[30:31], v[224:225]
	v_pk_fma_f32 v[234:235], v[86:87], v[30:31], v[234:235]
	v_add_f32_dpp v172, v172, v172 quad_perm:[2,3,0,1] row_mask:0xf bank_mask:0xf bound_ctrl:1
	v_add_f32_dpp v174, v174, v174 quad_perm:[2,3,0,1] row_mask:0xf bank_mask:0xf bound_ctrl:1
	v_add_f32_dpp v160, v160, v160 quad_perm:[2,3,0,1] row_mask:0xf bank_mask:0xf bound_ctrl:1
	v_add_f32_dpp v161, v161, v161 quad_perm:[2,3,0,1] row_mask:0xf bank_mask:0xf bound_ctrl:1
	v_add_f32_dpp v172, v172, v172 row_half_mirror row_mask:0xf bank_mask:0xf bound_ctrl:1
	v_add_f32_dpp v174, v174, v174 row_half_mirror row_mask:0xf bank_mask:0xf bound_ctrl:1
	v_add_f32_dpp v160, v160, v160 row_half_mirror row_mask:0xf bank_mask:0xf bound_ctrl:1
	v_add_f32_dpp v161, v161, v161 row_half_mirror row_mask:0xf bank_mask:0xf bound_ctrl:1
	s_waitcnt lgkmcnt(13)
	v_pk_fma_f32 v[72:73], v[32:33], v[172:173], v[218:219] op_sel_hi:[1,0,1]
	v_pk_fma_f32 v[80:81], v[32:33], v[174:175], v[226:227] op_sel_hi:[1,0,1]
	v_pk_fma_f32 v[74:75], v[34:35], v[172:173], v[220:221] op_sel_hi:[1,0,1]
	v_pk_fma_f32 v[82:83], v[34:35], v[174:175], v[228:229] op_sel_hi:[1,0,1]
	s_waitcnt lgkmcnt(12)
	v_pk_fma_f32 v[76:77], v[36:37], v[172:173], v[222:223] op_sel_hi:[1,0,1]
	v_pk_fma_f32 v[84:85], v[36:37], v[174:175], v[230:231] op_sel_hi:[1,0,1]
	v_pk_fma_f32 v[78:79], v[38:39], v[172:173], v[224:225] op_sel_hi:[1,0,1]
	v_pk_fma_f32 v[86:87], v[38:39], v[174:175], v[234:235] op_sel_hi:[1,0,1]
	ds_write_b64 v1, v[160:161] offset:54528
	s_waitcnt lgkmcnt(9)
	v_pk_mul_f32 v[164:165], v[72:73], v[176:177]
	v_pk_mul_f32 v[166:167], v[80:81], v[176:177]
	ds_read_b128 v[208:211], v2 offset:17408
	v_pk_mul_f32 v[168:169], v[72:73], v[48:49]
	v_pk_mul_f32 v[170:171], v[80:81], v[48:49]
	ds_read_b128 v[212:215], v2 offset:17424
	v_pk_fma_f32 v[164:165], v[74:75], v[178:179], v[164:165]
	v_pk_fma_f32 v[166:167], v[82:83], v[178:179], v[166:167]
	ds_read_b128 v[4:7], v2 offset:5376
	v_pk_fma_f32 v[168:169], v[74:75], v[50:51], v[168:169]
	v_pk_fma_f32 v[170:171], v[82:83], v[50:51], v[170:171]
	ds_read_b128 v[8:11], v2 offset:5392
	s_waitcnt lgkmcnt(12)
	v_pk_fma_f32 v[164:165], v[76:77], v[180:181], v[164:165]
	v_pk_fma_f32 v[166:167], v[84:85], v[180:181], v[166:167]
	ds_read_b128 v[40:43], v2 offset:13568
	v_pk_fma_f32 v[168:169], v[76:77], v[52:53], v[168:169]
	v_pk_fma_f32 v[170:171], v[84:85], v[52:53], v[170:171]
	ds_read_b128 v[44:47], v2 offset:13584
	v_pk_fma_f32 v[164:165], v[78:79], v[182:183], v[164:165]
	v_pk_fma_f32 v[166:167], v[86:87], v[182:183], v[166:167]
	ds_read_b64 v[26:27], v3 offset:42240
	v_pk_fma_f32 v[168:169], v[78:79], v[54:55], v[168:169]
	v_pk_fma_f32 v[170:171], v[86:87], v[54:55], v[170:171]
	ds_read_b128 v[12:15], v2 offset:1280
	s_waitcnt lgkmcnt(13)
	v_pk_mul_f32 v[218:219], v[216:217], v[200:201] op_sel_hi:[0,1]
	v_pk_mul_f32 v[226:227], v[216:217], v[200:201] op_sel:[1,0]
	ds_read_b128 v[28:31], v2 offset:1296
	v_pk_mul_f32 v[220:221], v[216:217], v[202:203] op_sel_hi:[0,1]
	v_pk_mul_f32 v[228:229], v[216:217], v[202:203] op_sel:[1,0]
	ds_read_b128 v[32:35], v2 offset:9472
	v_pk_mul_f32 v[222:223], v[216:217], v[204:205] op_sel_hi:[0,1]
	v_pk_mul_f32 v[230:231], v[216:217], v[204:205] op_sel:[1,0]
	ds_read_b128 v[36:39], v2 offset:9488
	v_pk_mul_f32 v[224:225], v[216:217], v[206:207] op_sel_hi:[0,1]
	v_pk_mul_f32 v[234:235], v[216:217], v[206:207] op_sel:[1,0]
	v_add_f32_e32 v172, v164, v165
	v_add_f32_e32 v174, v166, v167
	v_add_f32_e32 v160, v168, v169
	v_add_f32_e32 v161, v170, v171
	s_waitcnt lgkmcnt(15)
	v_pk_fma_f32 v[218:219], v[72:73], v[184:185], v[218:219]
	v_pk_fma_f32 v[226:227], v[80:81], v[184:185], v[226:227]
	v_pk_fma_f32 v[220:221], v[74:75], v[186:187], v[220:221]
	v_pk_fma_f32 v[228:229], v[82:83], v[186:187], v[228:229]
	v_add_f32_dpp v172, v172, v172 quad_perm:[1,0,3,2] row_mask:0xf bank_mask:0xf bound_ctrl:1
	v_add_f32_dpp v174, v174, v174 quad_perm:[1,0,3,2] row_mask:0xf bank_mask:0xf bound_ctrl:1
	v_add_f32_dpp v160, v160, v160 quad_perm:[1,0,3,2] row_mask:0xf bank_mask:0xf bound_ctrl:1
	v_add_f32_dpp v161, v161, v161 quad_perm:[1,0,3,2] row_mask:0xf bank_mask:0xf bound_ctrl:1
	s_waitcnt lgkmcnt(14)
	v_pk_fma_f32 v[222:223], v[76:77], v[188:189], v[222:223]
	v_pk_fma_f32 v[230:231], v[84:85], v[188:189], v[230:231]
	v_pk_fma_f32 v[224:225], v[78:79], v[190:191], v[224:225]
	v_pk_fma_f32 v[234:235], v[86:87], v[190:191], v[234:235]
	v_add_f32_dpp v172, v172, v172 quad_perm:[2,3,0,1] row_mask:0xf bank_mask:0xf bound_ctrl:1
	v_add_f32_dpp v174, v174, v174 quad_perm:[2,3,0,1] row_mask:0xf bank_mask:0xf bound_ctrl:1
	v_add_f32_dpp v160, v160, v160 quad_perm:[2,3,0,1] row_mask:0xf bank_mask:0xf bound_ctrl:1
	v_add_f32_dpp v161, v161, v161 quad_perm:[2,3,0,1] row_mask:0xf bank_mask:0xf bound_ctrl:1
	v_add_f32_dpp v172, v172, v172 row_half_mirror row_mask:0xf bank_mask:0xf bound_ctrl:1
	v_add_f32_dpp v174, v174, v174 row_half_mirror row_mask:0xf bank_mask:0xf bound_ctrl:1
	v_add_f32_dpp v160, v160, v160 row_half_mirror row_mask:0xf bank_mask:0xf bound_ctrl:1
	v_add_f32_dpp v161, v161, v161 row_half_mirror row_mask:0xf bank_mask:0xf bound_ctrl:1
	s_waitcnt lgkmcnt(13)
	v_pk_fma_f32 v[72:73], v[192:193], v[172:173], v[218:219] op_sel_hi:[1,0,1]
	v_pk_fma_f32 v[80:81], v[192:193], v[174:175], v[226:227] op_sel_hi:[1,0,1]
	v_pk_fma_f32 v[74:75], v[194:195], v[172:173], v[220:221] op_sel_hi:[1,0,1]
	v_pk_fma_f32 v[82:83], v[194:195], v[174:175], v[228:229] op_sel_hi:[1,0,1]
	s_waitcnt lgkmcnt(12)
	v_pk_fma_f32 v[76:77], v[196:197], v[172:173], v[222:223] op_sel_hi:[1,0,1]
	v_pk_fma_f32 v[84:85], v[196:197], v[174:175], v[230:231] op_sel_hi:[1,0,1]
	v_pk_fma_f32 v[78:79], v[198:199], v[172:173], v[224:225] op_sel_hi:[1,0,1]
	v_pk_fma_f32 v[86:87], v[198:199], v[174:175], v[234:235] op_sel_hi:[1,0,1]
	ds_write_b64 v1, v[160:161] offset:54784
	s_waitcnt lgkmcnt(9)
	v_pk_mul_f32 v[164:165], v[72:73], v[4:5]
	v_pk_mul_f32 v[166:167], v[80:81], v[4:5]
	ds_read_b128 v[48:51], v2 offset:17664
	v_pk_mul_f32 v[168:169], v[72:73], v[208:209]
	v_pk_mul_f32 v[170:171], v[80:81], v[208:209]
	ds_read_b128 v[52:55], v2 offset:17680
	v_pk_fma_f32 v[164:165], v[74:75], v[6:7], v[164:165]
	v_pk_fma_f32 v[166:167], v[82:83], v[6:7], v[166:167]
	ds_read_b128 v[176:179], v2 offset:5632
	v_pk_fma_f32 v[168:169], v[74:75], v[210:211], v[168:169]
	v_pk_fma_f32 v[170:171], v[82:83], v[210:211], v[170:171]
	ds_read_b128 v[180:183], v2 offset:5648
	s_waitcnt lgkmcnt(12)
	v_pk_fma_f32 v[164:165], v[76:77], v[8:9], v[164:165]
	v_pk_fma_f32 v[166:167], v[84:85], v[8:9], v[166:167]
	ds_read_b128 v[200:203], v2 offset:13824
	v_pk_fma_f32 v[168:169], v[76:77], v[212:213], v[168:169]
	v_pk_fma_f32 v[170:171], v[84:85], v[212:213], v[170:171]
	ds_read_b128 v[204:207], v2 offset:13840
	v_pk_fma_f32 v[164:165], v[78:79], v[10:11], v[164:165]
	v_pk_fma_f32 v[166:167], v[86:87], v[10:11], v[166:167]
	ds_read_b64 v[216:217], v3 offset:42496
	v_pk_fma_f32 v[168:169], v[78:79], v[214:215], v[168:169]
	v_pk_fma_f32 v[170:171], v[86:87], v[214:215], v[170:171]
	ds_read_b128 v[184:187], v2 offset:1536
	s_waitcnt lgkmcnt(13)
	v_pk_mul_f32 v[218:219], v[26:27], v[40:41] op_sel_hi:[0,1]
	v_pk_mul_f32 v[226:227], v[26:27], v[40:41] op_sel:[1,0]
	ds_read_b128 v[188:191], v2 offset:1552
	v_pk_mul_f32 v[220:221], v[26:27], v[42:43] op_sel_hi:[0,1]
	v_pk_mul_f32 v[228:229], v[26:27], v[42:43] op_sel:[1,0]
	ds_read_b128 v[192:195], v2 offset:9728
	v_pk_mul_f32 v[222:223], v[26:27], v[44:45] op_sel_hi:[0,1]
	v_pk_mul_f32 v[230:231], v[26:27], v[44:45] op_sel:[1,0]
	ds_read_b128 v[196:199], v2 offset:9744
	v_pk_mul_f32 v[224:225], v[26:27], v[46:47] op_sel_hi:[0,1]
	v_pk_mul_f32 v[234:235], v[26:27], v[46:47] op_sel:[1,0]
	v_add_f32_e32 v172, v164, v165
	v_add_f32_e32 v174, v166, v167
	v_add_f32_e32 v160, v168, v169
	v_add_f32_e32 v161, v170, v171
	s_waitcnt lgkmcnt(15)
	v_pk_fma_f32 v[218:219], v[72:73], v[12:13], v[218:219]
	v_pk_fma_f32 v[226:227], v[80:81], v[12:13], v[226:227]
	v_pk_fma_f32 v[220:221], v[74:75], v[14:15], v[220:221]
	v_pk_fma_f32 v[228:229], v[82:83], v[14:15], v[228:229]
	v_add_f32_dpp v172, v172, v172 quad_perm:[1,0,3,2] row_mask:0xf bank_mask:0xf bound_ctrl:1
	v_add_f32_dpp v174, v174, v174 quad_perm:[1,0,3,2] row_mask:0xf bank_mask:0xf bound_ctrl:1
	v_add_f32_dpp v160, v160, v160 quad_perm:[1,0,3,2] row_mask:0xf bank_mask:0xf bound_ctrl:1
	v_add_f32_dpp v161, v161, v161 quad_perm:[1,0,3,2] row_mask:0xf bank_mask:0xf bound_ctrl:1
	s_waitcnt lgkmcnt(14)
	v_pk_fma_f32 v[222:223], v[76:77], v[28:29], v[222:223]
	v_pk_fma_f32 v[230:231], v[84:85], v[28:29], v[230:231]
	v_pk_fma_f32 v[224:225], v[78:79], v[30:31], v[224:225]
	v_pk_fma_f32 v[234:235], v[86:87], v[30:31], v[234:235]
	v_add_f32_dpp v172, v172, v172 quad_perm:[2,3,0,1] row_mask:0xf bank_mask:0xf bound_ctrl:1
	v_add_f32_dpp v174, v174, v174 quad_perm:[2,3,0,1] row_mask:0xf bank_mask:0xf bound_ctrl:1
	v_add_f32_dpp v160, v160, v160 quad_perm:[2,3,0,1] row_mask:0xf bank_mask:0xf bound_ctrl:1
	v_add_f32_dpp v161, v161, v161 quad_perm:[2,3,0,1] row_mask:0xf bank_mask:0xf bound_ctrl:1
	v_add_f32_dpp v172, v172, v172 row_half_mirror row_mask:0xf bank_mask:0xf bound_ctrl:1
	v_add_f32_dpp v174, v174, v174 row_half_mirror row_mask:0xf bank_mask:0xf bound_ctrl:1
	v_add_f32_dpp v160, v160, v160 row_half_mirror row_mask:0xf bank_mask:0xf bound_ctrl:1
	v_add_f32_dpp v161, v161, v161 row_half_mirror row_mask:0xf bank_mask:0xf bound_ctrl:1
	s_waitcnt lgkmcnt(13)
	v_pk_fma_f32 v[72:73], v[32:33], v[172:173], v[218:219] op_sel_hi:[1,0,1]
	v_pk_fma_f32 v[80:81], v[32:33], v[174:175], v[226:227] op_sel_hi:[1,0,1]
	v_pk_fma_f32 v[74:75], v[34:35], v[172:173], v[220:221] op_sel_hi:[1,0,1]
	v_pk_fma_f32 v[82:83], v[34:35], v[174:175], v[228:229] op_sel_hi:[1,0,1]
	s_waitcnt lgkmcnt(12)
	v_pk_fma_f32 v[76:77], v[36:37], v[172:173], v[222:223] op_sel_hi:[1,0,1]
	v_pk_fma_f32 v[84:85], v[36:37], v[174:175], v[230:231] op_sel_hi:[1,0,1]
	v_pk_fma_f32 v[78:79], v[38:39], v[172:173], v[224:225] op_sel_hi:[1,0,1]
	v_pk_fma_f32 v[86:87], v[38:39], v[174:175], v[234:235] op_sel_hi:[1,0,1]
	ds_write_b64 v1, v[160:161] offset:55040
	s_waitcnt lgkmcnt(9)
	v_pk_mul_f32 v[164:165], v[72:73], v[176:177]
	v_pk_mul_f32 v[166:167], v[80:81], v[176:177]
	ds_read_b128 v[208:211], v2 offset:17920
	v_pk_mul_f32 v[168:169], v[72:73], v[48:49]
	v_pk_mul_f32 v[170:171], v[80:81], v[48:49]
	ds_read_b128 v[212:215], v2 offset:17936
	v_pk_fma_f32 v[164:165], v[74:75], v[178:179], v[164:165]
	v_pk_fma_f32 v[166:167], v[82:83], v[178:179], v[166:167]
	ds_read_b128 v[4:7], v2 offset:5888
	v_pk_fma_f32 v[168:169], v[74:75], v[50:51], v[168:169]
	v_pk_fma_f32 v[170:171], v[82:83], v[50:51], v[170:171]
	ds_read_b128 v[8:11], v2 offset:5904
	s_waitcnt lgkmcnt(12)
	v_pk_fma_f32 v[164:165], v[76:77], v[180:181], v[164:165]
	v_pk_fma_f32 v[166:167], v[84:85], v[180:181], v[166:167]
	ds_read_b128 v[40:43], v2 offset:14080
	v_pk_fma_f32 v[168:169], v[76:77], v[52:53], v[168:169]
	v_pk_fma_f32 v[170:171], v[84:85], v[52:53], v[170:171]
	ds_read_b128 v[44:47], v2 offset:14096
	v_pk_fma_f32 v[164:165], v[78:79], v[182:183], v[164:165]
	v_pk_fma_f32 v[166:167], v[86:87], v[182:183], v[166:167]
	ds_read_b64 v[26:27], v3 offset:42752
	v_pk_fma_f32 v[168:169], v[78:79], v[54:55], v[168:169]
	v_pk_fma_f32 v[170:171], v[86:87], v[54:55], v[170:171]
	ds_read_b128 v[12:15], v2 offset:1792
	s_waitcnt lgkmcnt(13)
	v_pk_mul_f32 v[218:219], v[216:217], v[200:201] op_sel_hi:[0,1]
	v_pk_mul_f32 v[226:227], v[216:217], v[200:201] op_sel:[1,0]
	ds_read_b128 v[28:31], v2 offset:1808
	v_pk_mul_f32 v[220:221], v[216:217], v[202:203] op_sel_hi:[0,1]
	v_pk_mul_f32 v[228:229], v[216:217], v[202:203] op_sel:[1,0]
	ds_read_b128 v[32:35], v2 offset:9984
	v_pk_mul_f32 v[222:223], v[216:217], v[204:205] op_sel_hi:[0,1]
	v_pk_mul_f32 v[230:231], v[216:217], v[204:205] op_sel:[1,0]
	ds_read_b128 v[36:39], v2 offset:10000
	v_pk_mul_f32 v[224:225], v[216:217], v[206:207] op_sel_hi:[0,1]
	v_pk_mul_f32 v[234:235], v[216:217], v[206:207] op_sel:[1,0]
	v_add_f32_e32 v172, v164, v165
	v_add_f32_e32 v174, v166, v167
	v_add_f32_e32 v160, v168, v169
	v_add_f32_e32 v161, v170, v171
	s_waitcnt lgkmcnt(15)
	v_pk_fma_f32 v[218:219], v[72:73], v[184:185], v[218:219]
	v_pk_fma_f32 v[226:227], v[80:81], v[184:185], v[226:227]
	v_pk_fma_f32 v[220:221], v[74:75], v[186:187], v[220:221]
	v_pk_fma_f32 v[228:229], v[82:83], v[186:187], v[228:229]
	v_add_f32_dpp v172, v172, v172 quad_perm:[1,0,3,2] row_mask:0xf bank_mask:0xf bound_ctrl:1
	v_add_f32_dpp v174, v174, v174 quad_perm:[1,0,3,2] row_mask:0xf bank_mask:0xf bound_ctrl:1
	v_add_f32_dpp v160, v160, v160 quad_perm:[1,0,3,2] row_mask:0xf bank_mask:0xf bound_ctrl:1
	v_add_f32_dpp v161, v161, v161 quad_perm:[1,0,3,2] row_mask:0xf bank_mask:0xf bound_ctrl:1
	s_waitcnt lgkmcnt(14)
	v_pk_fma_f32 v[222:223], v[76:77], v[188:189], v[222:223]
	v_pk_fma_f32 v[230:231], v[84:85], v[188:189], v[230:231]
	v_pk_fma_f32 v[224:225], v[78:79], v[190:191], v[224:225]
	v_pk_fma_f32 v[234:235], v[86:87], v[190:191], v[234:235]
	v_add_f32_dpp v172, v172, v172 quad_perm:[2,3,0,1] row_mask:0xf bank_mask:0xf bound_ctrl:1
	v_add_f32_dpp v174, v174, v174 quad_perm:[2,3,0,1] row_mask:0xf bank_mask:0xf bound_ctrl:1
	v_add_f32_dpp v160, v160, v160 quad_perm:[2,3,0,1] row_mask:0xf bank_mask:0xf bound_ctrl:1
	v_add_f32_dpp v161, v161, v161 quad_perm:[2,3,0,1] row_mask:0xf bank_mask:0xf bound_ctrl:1
	v_add_f32_dpp v172, v172, v172 row_half_mirror row_mask:0xf bank_mask:0xf bound_ctrl:1
	v_add_f32_dpp v174, v174, v174 row_half_mirror row_mask:0xf bank_mask:0xf bound_ctrl:1
	v_add_f32_dpp v160, v160, v160 row_half_mirror row_mask:0xf bank_mask:0xf bound_ctrl:1
	v_add_f32_dpp v161, v161, v161 row_half_mirror row_mask:0xf bank_mask:0xf bound_ctrl:1
	s_waitcnt lgkmcnt(13)
	v_pk_fma_f32 v[72:73], v[192:193], v[172:173], v[218:219] op_sel_hi:[1,0,1]
	v_pk_fma_f32 v[80:81], v[192:193], v[174:175], v[226:227] op_sel_hi:[1,0,1]
	v_pk_fma_f32 v[74:75], v[194:195], v[172:173], v[220:221] op_sel_hi:[1,0,1]
	v_pk_fma_f32 v[82:83], v[194:195], v[174:175], v[228:229] op_sel_hi:[1,0,1]
	s_waitcnt lgkmcnt(12)
	v_pk_fma_f32 v[76:77], v[196:197], v[172:173], v[222:223] op_sel_hi:[1,0,1]
	v_pk_fma_f32 v[84:85], v[196:197], v[174:175], v[230:231] op_sel_hi:[1,0,1]
	v_pk_fma_f32 v[78:79], v[198:199], v[172:173], v[224:225] op_sel_hi:[1,0,1]
	v_pk_fma_f32 v[86:87], v[198:199], v[174:175], v[234:235] op_sel_hi:[1,0,1]
	ds_write_b64 v1, v[160:161] offset:55296
	s_waitcnt lgkmcnt(9)
	v_pk_mul_f32 v[164:165], v[72:73], v[4:5]
	v_pk_mul_f32 v[166:167], v[80:81], v[4:5]
	ds_read_b128 v[48:51], v2 offset:18176
	v_pk_mul_f32 v[168:169], v[72:73], v[208:209]
	v_pk_mul_f32 v[170:171], v[80:81], v[208:209]
	ds_read_b128 v[52:55], v2 offset:18192
	v_pk_fma_f32 v[164:165], v[74:75], v[6:7], v[164:165]
	v_pk_fma_f32 v[166:167], v[82:83], v[6:7], v[166:167]
	ds_read_b128 v[176:179], v2 offset:6144
	v_pk_fma_f32 v[168:169], v[74:75], v[210:211], v[168:169]
	v_pk_fma_f32 v[170:171], v[82:83], v[210:211], v[170:171]
	ds_read_b128 v[180:183], v2 offset:6160
	s_waitcnt lgkmcnt(12)
	v_pk_fma_f32 v[164:165], v[76:77], v[8:9], v[164:165]
	v_pk_fma_f32 v[166:167], v[84:85], v[8:9], v[166:167]
	ds_read_b128 v[200:203], v2 offset:14336
	v_pk_fma_f32 v[168:169], v[76:77], v[212:213], v[168:169]
	v_pk_fma_f32 v[170:171], v[84:85], v[212:213], v[170:171]
	ds_read_b128 v[204:207], v2 offset:14352
	v_pk_fma_f32 v[164:165], v[78:79], v[10:11], v[164:165]
	v_pk_fma_f32 v[166:167], v[86:87], v[10:11], v[166:167]
	ds_read_b64 v[216:217], v3 offset:43008
	v_pk_fma_f32 v[168:169], v[78:79], v[214:215], v[168:169]
	v_pk_fma_f32 v[170:171], v[86:87], v[214:215], v[170:171]
	ds_read_b128 v[184:187], v2 offset:2048
	s_waitcnt lgkmcnt(13)
	v_pk_mul_f32 v[218:219], v[26:27], v[40:41] op_sel_hi:[0,1]
	v_pk_mul_f32 v[226:227], v[26:27], v[40:41] op_sel:[1,0]
	ds_read_b128 v[188:191], v2 offset:2064
	v_pk_mul_f32 v[220:221], v[26:27], v[42:43] op_sel_hi:[0,1]
	v_pk_mul_f32 v[228:229], v[26:27], v[42:43] op_sel:[1,0]
	ds_read_b128 v[192:195], v2 offset:10240
	v_pk_mul_f32 v[222:223], v[26:27], v[44:45] op_sel_hi:[0,1]
	v_pk_mul_f32 v[230:231], v[26:27], v[44:45] op_sel:[1,0]
	ds_read_b128 v[196:199], v2 offset:10256
	v_pk_mul_f32 v[224:225], v[26:27], v[46:47] op_sel_hi:[0,1]
	v_pk_mul_f32 v[234:235], v[26:27], v[46:47] op_sel:[1,0]
	v_add_f32_e32 v172, v164, v165
	v_add_f32_e32 v174, v166, v167
	v_add_f32_e32 v160, v168, v169
	v_add_f32_e32 v161, v170, v171
	s_waitcnt lgkmcnt(15)
	v_pk_fma_f32 v[218:219], v[72:73], v[12:13], v[218:219]
	v_pk_fma_f32 v[226:227], v[80:81], v[12:13], v[226:227]
	v_pk_fma_f32 v[220:221], v[74:75], v[14:15], v[220:221]
	v_pk_fma_f32 v[228:229], v[82:83], v[14:15], v[228:229]
	v_add_f32_dpp v172, v172, v172 quad_perm:[1,0,3,2] row_mask:0xf bank_mask:0xf bound_ctrl:1
	v_add_f32_dpp v174, v174, v174 quad_perm:[1,0,3,2] row_mask:0xf bank_mask:0xf bound_ctrl:1
	v_add_f32_dpp v160, v160, v160 quad_perm:[1,0,3,2] row_mask:0xf bank_mask:0xf bound_ctrl:1
	v_add_f32_dpp v161, v161, v161 quad_perm:[1,0,3,2] row_mask:0xf bank_mask:0xf bound_ctrl:1
	s_waitcnt lgkmcnt(14)
	v_pk_fma_f32 v[222:223], v[76:77], v[28:29], v[222:223]
	v_pk_fma_f32 v[230:231], v[84:85], v[28:29], v[230:231]
	v_pk_fma_f32 v[224:225], v[78:79], v[30:31], v[224:225]
	v_pk_fma_f32 v[234:235], v[86:87], v[30:31], v[234:235]
	v_add_f32_dpp v172, v172, v172 quad_perm:[2,3,0,1] row_mask:0xf bank_mask:0xf bound_ctrl:1
	v_add_f32_dpp v174, v174, v174 quad_perm:[2,3,0,1] row_mask:0xf bank_mask:0xf bound_ctrl:1
	v_add_f32_dpp v160, v160, v160 quad_perm:[2,3,0,1] row_mask:0xf bank_mask:0xf bound_ctrl:1
	v_add_f32_dpp v161, v161, v161 quad_perm:[2,3,0,1] row_mask:0xf bank_mask:0xf bound_ctrl:1
	v_add_f32_dpp v172, v172, v172 row_half_mirror row_mask:0xf bank_mask:0xf bound_ctrl:1
	v_add_f32_dpp v174, v174, v174 row_half_mirror row_mask:0xf bank_mask:0xf bound_ctrl:1
	v_add_f32_dpp v160, v160, v160 row_half_mirror row_mask:0xf bank_mask:0xf bound_ctrl:1
	v_add_f32_dpp v161, v161, v161 row_half_mirror row_mask:0xf bank_mask:0xf bound_ctrl:1
	s_waitcnt lgkmcnt(13)
	v_pk_fma_f32 v[72:73], v[32:33], v[172:173], v[218:219] op_sel_hi:[1,0,1]
	v_pk_fma_f32 v[80:81], v[32:33], v[174:175], v[226:227] op_sel_hi:[1,0,1]
	v_pk_fma_f32 v[74:75], v[34:35], v[172:173], v[220:221] op_sel_hi:[1,0,1]
	v_pk_fma_f32 v[82:83], v[34:35], v[174:175], v[228:229] op_sel_hi:[1,0,1]
	s_waitcnt lgkmcnt(12)
	v_pk_fma_f32 v[76:77], v[36:37], v[172:173], v[222:223] op_sel_hi:[1,0,1]
	v_pk_fma_f32 v[84:85], v[36:37], v[174:175], v[230:231] op_sel_hi:[1,0,1]
	v_pk_fma_f32 v[78:79], v[38:39], v[172:173], v[224:225] op_sel_hi:[1,0,1]
	v_pk_fma_f32 v[86:87], v[38:39], v[174:175], v[234:235] op_sel_hi:[1,0,1]
	ds_write_b64 v1, v[160:161] offset:55552
	s_waitcnt lgkmcnt(9)
	v_pk_mul_f32 v[164:165], v[72:73], v[176:177]
	v_pk_mul_f32 v[166:167], v[80:81], v[176:177]
	ds_read_b128 v[208:211], v2 offset:18432
	v_pk_mul_f32 v[168:169], v[72:73], v[48:49]
	v_pk_mul_f32 v[170:171], v[80:81], v[48:49]
	ds_read_b128 v[212:215], v2 offset:18448
	v_pk_fma_f32 v[164:165], v[74:75], v[178:179], v[164:165]
	v_pk_fma_f32 v[166:167], v[82:83], v[178:179], v[166:167]
	ds_read_b128 v[4:7], v2 offset:6400
	v_pk_fma_f32 v[168:169], v[74:75], v[50:51], v[168:169]
	v_pk_fma_f32 v[170:171], v[82:83], v[50:51], v[170:171]
	ds_read_b128 v[8:11], v2 offset:6416
	s_waitcnt lgkmcnt(12)
	v_pk_fma_f32 v[164:165], v[76:77], v[180:181], v[164:165]
	v_pk_fma_f32 v[166:167], v[84:85], v[180:181], v[166:167]
	ds_read_b128 v[40:43], v2 offset:14592
	v_pk_fma_f32 v[168:169], v[76:77], v[52:53], v[168:169]
	v_pk_fma_f32 v[170:171], v[84:85], v[52:53], v[170:171]
	ds_read_b128 v[44:47], v2 offset:14608
	v_pk_fma_f32 v[164:165], v[78:79], v[182:183], v[164:165]
	v_pk_fma_f32 v[166:167], v[86:87], v[182:183], v[166:167]
	ds_read_b64 v[26:27], v3 offset:43264
	v_pk_fma_f32 v[168:169], v[78:79], v[54:55], v[168:169]
	v_pk_fma_f32 v[170:171], v[86:87], v[54:55], v[170:171]
	ds_read_b128 v[12:15], v2 offset:2304
	s_waitcnt lgkmcnt(13)
	v_pk_mul_f32 v[218:219], v[216:217], v[200:201] op_sel_hi:[0,1]
	v_pk_mul_f32 v[226:227], v[216:217], v[200:201] op_sel:[1,0]
	ds_read_b128 v[28:31], v2 offset:2320
	v_pk_mul_f32 v[220:221], v[216:217], v[202:203] op_sel_hi:[0,1]
	v_pk_mul_f32 v[228:229], v[216:217], v[202:203] op_sel:[1,0]
	ds_read_b128 v[32:35], v2 offset:10496
	v_pk_mul_f32 v[222:223], v[216:217], v[204:205] op_sel_hi:[0,1]
	v_pk_mul_f32 v[230:231], v[216:217], v[204:205] op_sel:[1,0]
	ds_read_b128 v[36:39], v2 offset:10512
	v_pk_mul_f32 v[224:225], v[216:217], v[206:207] op_sel_hi:[0,1]
	v_pk_mul_f32 v[234:235], v[216:217], v[206:207] op_sel:[1,0]
	v_add_f32_e32 v172, v164, v165
	v_add_f32_e32 v174, v166, v167
	v_add_f32_e32 v160, v168, v169
	v_add_f32_e32 v161, v170, v171
	s_waitcnt lgkmcnt(15)
	v_pk_fma_f32 v[218:219], v[72:73], v[184:185], v[218:219]
	v_pk_fma_f32 v[226:227], v[80:81], v[184:185], v[226:227]
	v_pk_fma_f32 v[220:221], v[74:75], v[186:187], v[220:221]
	v_pk_fma_f32 v[228:229], v[82:83], v[186:187], v[228:229]
	v_add_f32_dpp v172, v172, v172 quad_perm:[1,0,3,2] row_mask:0xf bank_mask:0xf bound_ctrl:1
	v_add_f32_dpp v174, v174, v174 quad_perm:[1,0,3,2] row_mask:0xf bank_mask:0xf bound_ctrl:1
	v_add_f32_dpp v160, v160, v160 quad_perm:[1,0,3,2] row_mask:0xf bank_mask:0xf bound_ctrl:1
	v_add_f32_dpp v161, v161, v161 quad_perm:[1,0,3,2] row_mask:0xf bank_mask:0xf bound_ctrl:1
	s_waitcnt lgkmcnt(14)
	v_pk_fma_f32 v[222:223], v[76:77], v[188:189], v[222:223]
	v_pk_fma_f32 v[230:231], v[84:85], v[188:189], v[230:231]
	v_pk_fma_f32 v[224:225], v[78:79], v[190:191], v[224:225]
	v_pk_fma_f32 v[234:235], v[86:87], v[190:191], v[234:235]
	v_add_f32_dpp v172, v172, v172 quad_perm:[2,3,0,1] row_mask:0xf bank_mask:0xf bound_ctrl:1
	v_add_f32_dpp v174, v174, v174 quad_perm:[2,3,0,1] row_mask:0xf bank_mask:0xf bound_ctrl:1
	v_add_f32_dpp v160, v160, v160 quad_perm:[2,3,0,1] row_mask:0xf bank_mask:0xf bound_ctrl:1
	v_add_f32_dpp v161, v161, v161 quad_perm:[2,3,0,1] row_mask:0xf bank_mask:0xf bound_ctrl:1
	v_add_f32_dpp v172, v172, v172 row_half_mirror row_mask:0xf bank_mask:0xf bound_ctrl:1
	v_add_f32_dpp v174, v174, v174 row_half_mirror row_mask:0xf bank_mask:0xf bound_ctrl:1
	v_add_f32_dpp v160, v160, v160 row_half_mirror row_mask:0xf bank_mask:0xf bound_ctrl:1
	v_add_f32_dpp v161, v161, v161 row_half_mirror row_mask:0xf bank_mask:0xf bound_ctrl:1
	s_waitcnt lgkmcnt(13)
	v_pk_fma_f32 v[72:73], v[192:193], v[172:173], v[218:219] op_sel_hi:[1,0,1]
	v_pk_fma_f32 v[80:81], v[192:193], v[174:175], v[226:227] op_sel_hi:[1,0,1]
	v_pk_fma_f32 v[74:75], v[194:195], v[172:173], v[220:221] op_sel_hi:[1,0,1]
	v_pk_fma_f32 v[82:83], v[194:195], v[174:175], v[228:229] op_sel_hi:[1,0,1]
	s_waitcnt lgkmcnt(12)
	v_pk_fma_f32 v[76:77], v[196:197], v[172:173], v[222:223] op_sel_hi:[1,0,1]
	v_pk_fma_f32 v[84:85], v[196:197], v[174:175], v[230:231] op_sel_hi:[1,0,1]
	v_pk_fma_f32 v[78:79], v[198:199], v[172:173], v[224:225] op_sel_hi:[1,0,1]
	v_pk_fma_f32 v[86:87], v[198:199], v[174:175], v[234:235] op_sel_hi:[1,0,1]
	ds_write_b64 v1, v[160:161] offset:55808
	s_waitcnt lgkmcnt(9)
	v_pk_mul_f32 v[164:165], v[72:73], v[4:5]
	v_pk_mul_f32 v[166:167], v[80:81], v[4:5]
	ds_read_b128 v[48:51], v2 offset:18688
	v_pk_mul_f32 v[168:169], v[72:73], v[208:209]
	v_pk_mul_f32 v[170:171], v[80:81], v[208:209]
	ds_read_b128 v[52:55], v2 offset:18704
	v_pk_fma_f32 v[164:165], v[74:75], v[6:7], v[164:165]
	v_pk_fma_f32 v[166:167], v[82:83], v[6:7], v[166:167]
	ds_read_b128 v[176:179], v2 offset:6656
	v_pk_fma_f32 v[168:169], v[74:75], v[210:211], v[168:169]
	v_pk_fma_f32 v[170:171], v[82:83], v[210:211], v[170:171]
	ds_read_b128 v[180:183], v2 offset:6672
	s_waitcnt lgkmcnt(12)
	v_pk_fma_f32 v[164:165], v[76:77], v[8:9], v[164:165]
	v_pk_fma_f32 v[166:167], v[84:85], v[8:9], v[166:167]
	ds_read_b128 v[200:203], v2 offset:14848
	v_pk_fma_f32 v[168:169], v[76:77], v[212:213], v[168:169]
	v_pk_fma_f32 v[170:171], v[84:85], v[212:213], v[170:171]
	ds_read_b128 v[204:207], v2 offset:14864
	v_pk_fma_f32 v[164:165], v[78:79], v[10:11], v[164:165]
	v_pk_fma_f32 v[166:167], v[86:87], v[10:11], v[166:167]
	ds_read_b64 v[216:217], v3 offset:43520
	v_pk_fma_f32 v[168:169], v[78:79], v[214:215], v[168:169]
	v_pk_fma_f32 v[170:171], v[86:87], v[214:215], v[170:171]
	ds_read_b128 v[184:187], v2 offset:2560
	s_waitcnt lgkmcnt(13)
	v_pk_mul_f32 v[218:219], v[26:27], v[40:41] op_sel_hi:[0,1]
	v_pk_mul_f32 v[226:227], v[26:27], v[40:41] op_sel:[1,0]
	ds_read_b128 v[188:191], v2 offset:2576
	v_pk_mul_f32 v[220:221], v[26:27], v[42:43] op_sel_hi:[0,1]
	v_pk_mul_f32 v[228:229], v[26:27], v[42:43] op_sel:[1,0]
	ds_read_b128 v[192:195], v2 offset:10752
	v_pk_mul_f32 v[222:223], v[26:27], v[44:45] op_sel_hi:[0,1]
	v_pk_mul_f32 v[230:231], v[26:27], v[44:45] op_sel:[1,0]
	ds_read_b128 v[196:199], v2 offset:10768
	v_pk_mul_f32 v[224:225], v[26:27], v[46:47] op_sel_hi:[0,1]
	v_pk_mul_f32 v[234:235], v[26:27], v[46:47] op_sel:[1,0]
	v_add_f32_e32 v172, v164, v165
	v_add_f32_e32 v174, v166, v167
	v_add_f32_e32 v160, v168, v169
	v_add_f32_e32 v161, v170, v171
	s_waitcnt lgkmcnt(15)
	v_pk_fma_f32 v[218:219], v[72:73], v[12:13], v[218:219]
	v_pk_fma_f32 v[226:227], v[80:81], v[12:13], v[226:227]
	v_pk_fma_f32 v[220:221], v[74:75], v[14:15], v[220:221]
	v_pk_fma_f32 v[228:229], v[82:83], v[14:15], v[228:229]
	v_add_f32_dpp v172, v172, v172 quad_perm:[1,0,3,2] row_mask:0xf bank_mask:0xf bound_ctrl:1
	v_add_f32_dpp v174, v174, v174 quad_perm:[1,0,3,2] row_mask:0xf bank_mask:0xf bound_ctrl:1
	v_add_f32_dpp v160, v160, v160 quad_perm:[1,0,3,2] row_mask:0xf bank_mask:0xf bound_ctrl:1
	v_add_f32_dpp v161, v161, v161 quad_perm:[1,0,3,2] row_mask:0xf bank_mask:0xf bound_ctrl:1
	s_waitcnt lgkmcnt(14)
	v_pk_fma_f32 v[222:223], v[76:77], v[28:29], v[222:223]
	v_pk_fma_f32 v[230:231], v[84:85], v[28:29], v[230:231]
	v_pk_fma_f32 v[224:225], v[78:79], v[30:31], v[224:225]
	v_pk_fma_f32 v[234:235], v[86:87], v[30:31], v[234:235]
	v_add_f32_dpp v172, v172, v172 quad_perm:[2,3,0,1] row_mask:0xf bank_mask:0xf bound_ctrl:1
	v_add_f32_dpp v174, v174, v174 quad_perm:[2,3,0,1] row_mask:0xf bank_mask:0xf bound_ctrl:1
	v_add_f32_dpp v160, v160, v160 quad_perm:[2,3,0,1] row_mask:0xf bank_mask:0xf bound_ctrl:1
	v_add_f32_dpp v161, v161, v161 quad_perm:[2,3,0,1] row_mask:0xf bank_mask:0xf bound_ctrl:1
	v_add_f32_dpp v172, v172, v172 row_half_mirror row_mask:0xf bank_mask:0xf bound_ctrl:1
	v_add_f32_dpp v174, v174, v174 row_half_mirror row_mask:0xf bank_mask:0xf bound_ctrl:1
	v_add_f32_dpp v160, v160, v160 row_half_mirror row_mask:0xf bank_mask:0xf bound_ctrl:1
	v_add_f32_dpp v161, v161, v161 row_half_mirror row_mask:0xf bank_mask:0xf bound_ctrl:1
	s_waitcnt lgkmcnt(13)
	v_pk_fma_f32 v[72:73], v[32:33], v[172:173], v[218:219] op_sel_hi:[1,0,1]
	v_pk_fma_f32 v[80:81], v[32:33], v[174:175], v[226:227] op_sel_hi:[1,0,1]
	v_pk_fma_f32 v[74:75], v[34:35], v[172:173], v[220:221] op_sel_hi:[1,0,1]
	v_pk_fma_f32 v[82:83], v[34:35], v[174:175], v[228:229] op_sel_hi:[1,0,1]
	s_waitcnt lgkmcnt(12)
	v_pk_fma_f32 v[76:77], v[36:37], v[172:173], v[222:223] op_sel_hi:[1,0,1]
	v_pk_fma_f32 v[84:85], v[36:37], v[174:175], v[230:231] op_sel_hi:[1,0,1]
	v_pk_fma_f32 v[78:79], v[38:39], v[172:173], v[224:225] op_sel_hi:[1,0,1]
	v_pk_fma_f32 v[86:87], v[38:39], v[174:175], v[234:235] op_sel_hi:[1,0,1]
	ds_write_b64 v1, v[160:161] offset:56064
	s_waitcnt lgkmcnt(9)
	v_pk_mul_f32 v[164:165], v[72:73], v[176:177]
	v_pk_mul_f32 v[166:167], v[80:81], v[176:177]
	ds_read_b128 v[208:211], v2 offset:18944
	v_pk_mul_f32 v[168:169], v[72:73], v[48:49]
	v_pk_mul_f32 v[170:171], v[80:81], v[48:49]
	ds_read_b128 v[212:215], v2 offset:18960
	v_pk_fma_f32 v[164:165], v[74:75], v[178:179], v[164:165]
	v_pk_fma_f32 v[166:167], v[82:83], v[178:179], v[166:167]
	ds_read_b128 v[4:7], v2 offset:6912
	v_pk_fma_f32 v[168:169], v[74:75], v[50:51], v[168:169]
	v_pk_fma_f32 v[170:171], v[82:83], v[50:51], v[170:171]
	ds_read_b128 v[8:11], v2 offset:6928
	s_waitcnt lgkmcnt(12)
	v_pk_fma_f32 v[164:165], v[76:77], v[180:181], v[164:165]
	v_pk_fma_f32 v[166:167], v[84:85], v[180:181], v[166:167]
	ds_read_b128 v[40:43], v2 offset:15104
	v_pk_fma_f32 v[168:169], v[76:77], v[52:53], v[168:169]
	v_pk_fma_f32 v[170:171], v[84:85], v[52:53], v[170:171]
	ds_read_b128 v[44:47], v2 offset:15120
	v_pk_fma_f32 v[164:165], v[78:79], v[182:183], v[164:165]
	v_pk_fma_f32 v[166:167], v[86:87], v[182:183], v[166:167]
	ds_read_b64 v[26:27], v3 offset:43776
	v_pk_fma_f32 v[168:169], v[78:79], v[54:55], v[168:169]
	v_pk_fma_f32 v[170:171], v[86:87], v[54:55], v[170:171]
	ds_read_b128 v[12:15], v2 offset:2816
	s_waitcnt lgkmcnt(13)
	v_pk_mul_f32 v[218:219], v[216:217], v[200:201] op_sel_hi:[0,1]
	v_pk_mul_f32 v[226:227], v[216:217], v[200:201] op_sel:[1,0]
	ds_read_b128 v[28:31], v2 offset:2832
	v_pk_mul_f32 v[220:221], v[216:217], v[202:203] op_sel_hi:[0,1]
	v_pk_mul_f32 v[228:229], v[216:217], v[202:203] op_sel:[1,0]
	ds_read_b128 v[32:35], v2 offset:11008
	v_pk_mul_f32 v[222:223], v[216:217], v[204:205] op_sel_hi:[0,1]
	v_pk_mul_f32 v[230:231], v[216:217], v[204:205] op_sel:[1,0]
	ds_read_b128 v[36:39], v2 offset:11024
	v_pk_mul_f32 v[224:225], v[216:217], v[206:207] op_sel_hi:[0,1]
	v_pk_mul_f32 v[234:235], v[216:217], v[206:207] op_sel:[1,0]
	v_add_f32_e32 v172, v164, v165
	v_add_f32_e32 v174, v166, v167
	v_add_f32_e32 v160, v168, v169
	v_add_f32_e32 v161, v170, v171
	s_waitcnt lgkmcnt(15)
	v_pk_fma_f32 v[218:219], v[72:73], v[184:185], v[218:219]
	v_pk_fma_f32 v[226:227], v[80:81], v[184:185], v[226:227]
	v_pk_fma_f32 v[220:221], v[74:75], v[186:187], v[220:221]
	v_pk_fma_f32 v[228:229], v[82:83], v[186:187], v[228:229]
	v_add_f32_dpp v172, v172, v172 quad_perm:[1,0,3,2] row_mask:0xf bank_mask:0xf bound_ctrl:1
	v_add_f32_dpp v174, v174, v174 quad_perm:[1,0,3,2] row_mask:0xf bank_mask:0xf bound_ctrl:1
	v_add_f32_dpp v160, v160, v160 quad_perm:[1,0,3,2] row_mask:0xf bank_mask:0xf bound_ctrl:1
	v_add_f32_dpp v161, v161, v161 quad_perm:[1,0,3,2] row_mask:0xf bank_mask:0xf bound_ctrl:1
	s_waitcnt lgkmcnt(14)
	v_pk_fma_f32 v[222:223], v[76:77], v[188:189], v[222:223]
	v_pk_fma_f32 v[230:231], v[84:85], v[188:189], v[230:231]
	v_pk_fma_f32 v[224:225], v[78:79], v[190:191], v[224:225]
	v_pk_fma_f32 v[234:235], v[86:87], v[190:191], v[234:235]
	v_add_f32_dpp v172, v172, v172 quad_perm:[2,3,0,1] row_mask:0xf bank_mask:0xf bound_ctrl:1
	v_add_f32_dpp v174, v174, v174 quad_perm:[2,3,0,1] row_mask:0xf bank_mask:0xf bound_ctrl:1
	v_add_f32_dpp v160, v160, v160 quad_perm:[2,3,0,1] row_mask:0xf bank_mask:0xf bound_ctrl:1
	v_add_f32_dpp v161, v161, v161 quad_perm:[2,3,0,1] row_mask:0xf bank_mask:0xf bound_ctrl:1
	v_add_f32_dpp v172, v172, v172 row_half_mirror row_mask:0xf bank_mask:0xf bound_ctrl:1
	v_add_f32_dpp v174, v174, v174 row_half_mirror row_mask:0xf bank_mask:0xf bound_ctrl:1
	v_add_f32_dpp v160, v160, v160 row_half_mirror row_mask:0xf bank_mask:0xf bound_ctrl:1
	v_add_f32_dpp v161, v161, v161 row_half_mirror row_mask:0xf bank_mask:0xf bound_ctrl:1
	s_waitcnt lgkmcnt(13)
	v_pk_fma_f32 v[72:73], v[192:193], v[172:173], v[218:219] op_sel_hi:[1,0,1]
	v_pk_fma_f32 v[80:81], v[192:193], v[174:175], v[226:227] op_sel_hi:[1,0,1]
	v_pk_fma_f32 v[74:75], v[194:195], v[172:173], v[220:221] op_sel_hi:[1,0,1]
	v_pk_fma_f32 v[82:83], v[194:195], v[174:175], v[228:229] op_sel_hi:[1,0,1]
	s_waitcnt lgkmcnt(12)
	v_pk_fma_f32 v[76:77], v[196:197], v[172:173], v[222:223] op_sel_hi:[1,0,1]
	v_pk_fma_f32 v[84:85], v[196:197], v[174:175], v[230:231] op_sel_hi:[1,0,1]
	v_pk_fma_f32 v[78:79], v[198:199], v[172:173], v[224:225] op_sel_hi:[1,0,1]
	v_pk_fma_f32 v[86:87], v[198:199], v[174:175], v[234:235] op_sel_hi:[1,0,1]
	ds_write_b64 v1, v[160:161] offset:56320
	s_waitcnt lgkmcnt(9)
	v_pk_mul_f32 v[164:165], v[72:73], v[4:5]
	v_pk_mul_f32 v[166:167], v[80:81], v[4:5]
	ds_read_b128 v[48:51], v2 offset:19200
	v_pk_mul_f32 v[168:169], v[72:73], v[208:209]
	v_pk_mul_f32 v[170:171], v[80:81], v[208:209]
	ds_read_b128 v[52:55], v2 offset:19216
	v_pk_fma_f32 v[164:165], v[74:75], v[6:7], v[164:165]
	v_pk_fma_f32 v[166:167], v[82:83], v[6:7], v[166:167]
	ds_read_b128 v[176:179], v2 offset:7168
	v_pk_fma_f32 v[168:169], v[74:75], v[210:211], v[168:169]
	v_pk_fma_f32 v[170:171], v[82:83], v[210:211], v[170:171]
	ds_read_b128 v[180:183], v2 offset:7184
	s_waitcnt lgkmcnt(12)
	v_pk_fma_f32 v[164:165], v[76:77], v[8:9], v[164:165]
	v_pk_fma_f32 v[166:167], v[84:85], v[8:9], v[166:167]
	ds_read_b128 v[200:203], v2 offset:15360
	v_pk_fma_f32 v[168:169], v[76:77], v[212:213], v[168:169]
	v_pk_fma_f32 v[170:171], v[84:85], v[212:213], v[170:171]
	ds_read_b128 v[204:207], v2 offset:15376
	v_pk_fma_f32 v[164:165], v[78:79], v[10:11], v[164:165]
	v_pk_fma_f32 v[166:167], v[86:87], v[10:11], v[166:167]
	ds_read_b64 v[216:217], v3 offset:44032
	v_pk_fma_f32 v[168:169], v[78:79], v[214:215], v[168:169]
	v_pk_fma_f32 v[170:171], v[86:87], v[214:215], v[170:171]
	ds_read_b128 v[184:187], v2 offset:3072
	s_waitcnt lgkmcnt(13)
	v_pk_mul_f32 v[218:219], v[26:27], v[40:41] op_sel_hi:[0,1]
	v_pk_mul_f32 v[226:227], v[26:27], v[40:41] op_sel:[1,0]
	ds_read_b128 v[188:191], v2 offset:3088
	v_pk_mul_f32 v[220:221], v[26:27], v[42:43] op_sel_hi:[0,1]
	v_pk_mul_f32 v[228:229], v[26:27], v[42:43] op_sel:[1,0]
	ds_read_b128 v[192:195], v2 offset:11264
	v_pk_mul_f32 v[222:223], v[26:27], v[44:45] op_sel_hi:[0,1]
	v_pk_mul_f32 v[230:231], v[26:27], v[44:45] op_sel:[1,0]
	ds_read_b128 v[196:199], v2 offset:11280
	v_pk_mul_f32 v[224:225], v[26:27], v[46:47] op_sel_hi:[0,1]
	v_pk_mul_f32 v[234:235], v[26:27], v[46:47] op_sel:[1,0]
	v_add_f32_e32 v172, v164, v165
	v_add_f32_e32 v174, v166, v167
	v_add_f32_e32 v160, v168, v169
	v_add_f32_e32 v161, v170, v171
	s_waitcnt lgkmcnt(15)
	v_pk_fma_f32 v[218:219], v[72:73], v[12:13], v[218:219]
	v_pk_fma_f32 v[226:227], v[80:81], v[12:13], v[226:227]
	v_pk_fma_f32 v[220:221], v[74:75], v[14:15], v[220:221]
	v_pk_fma_f32 v[228:229], v[82:83], v[14:15], v[228:229]
	v_add_f32_dpp v172, v172, v172 quad_perm:[1,0,3,2] row_mask:0xf bank_mask:0xf bound_ctrl:1
	v_add_f32_dpp v174, v174, v174 quad_perm:[1,0,3,2] row_mask:0xf bank_mask:0xf bound_ctrl:1
	v_add_f32_dpp v160, v160, v160 quad_perm:[1,0,3,2] row_mask:0xf bank_mask:0xf bound_ctrl:1
	v_add_f32_dpp v161, v161, v161 quad_perm:[1,0,3,2] row_mask:0xf bank_mask:0xf bound_ctrl:1
	s_waitcnt lgkmcnt(14)
	v_pk_fma_f32 v[222:223], v[76:77], v[28:29], v[222:223]
	v_pk_fma_f32 v[230:231], v[84:85], v[28:29], v[230:231]
	v_pk_fma_f32 v[224:225], v[78:79], v[30:31], v[224:225]
	v_pk_fma_f32 v[234:235], v[86:87], v[30:31], v[234:235]
	v_add_f32_dpp v172, v172, v172 quad_perm:[2,3,0,1] row_mask:0xf bank_mask:0xf bound_ctrl:1
	v_add_f32_dpp v174, v174, v174 quad_perm:[2,3,0,1] row_mask:0xf bank_mask:0xf bound_ctrl:1
	v_add_f32_dpp v160, v160, v160 quad_perm:[2,3,0,1] row_mask:0xf bank_mask:0xf bound_ctrl:1
	v_add_f32_dpp v161, v161, v161 quad_perm:[2,3,0,1] row_mask:0xf bank_mask:0xf bound_ctrl:1
	v_add_f32_dpp v172, v172, v172 row_half_mirror row_mask:0xf bank_mask:0xf bound_ctrl:1
	v_add_f32_dpp v174, v174, v174 row_half_mirror row_mask:0xf bank_mask:0xf bound_ctrl:1
	v_add_f32_dpp v160, v160, v160 row_half_mirror row_mask:0xf bank_mask:0xf bound_ctrl:1
	v_add_f32_dpp v161, v161, v161 row_half_mirror row_mask:0xf bank_mask:0xf bound_ctrl:1
	s_waitcnt lgkmcnt(13)
	v_pk_fma_f32 v[72:73], v[32:33], v[172:173], v[218:219] op_sel_hi:[1,0,1]
	v_pk_fma_f32 v[80:81], v[32:33], v[174:175], v[226:227] op_sel_hi:[1,0,1]
	v_pk_fma_f32 v[74:75], v[34:35], v[172:173], v[220:221] op_sel_hi:[1,0,1]
	v_pk_fma_f32 v[82:83], v[34:35], v[174:175], v[228:229] op_sel_hi:[1,0,1]
	s_waitcnt lgkmcnt(12)
	v_pk_fma_f32 v[76:77], v[36:37], v[172:173], v[222:223] op_sel_hi:[1,0,1]
	v_pk_fma_f32 v[84:85], v[36:37], v[174:175], v[230:231] op_sel_hi:[1,0,1]
	v_pk_fma_f32 v[78:79], v[38:39], v[172:173], v[224:225] op_sel_hi:[1,0,1]
	v_pk_fma_f32 v[86:87], v[38:39], v[174:175], v[234:235] op_sel_hi:[1,0,1]
	ds_write_b64 v1, v[160:161] offset:56576
	s_waitcnt lgkmcnt(9)
	v_pk_mul_f32 v[164:165], v[72:73], v[176:177]
	v_pk_mul_f32 v[166:167], v[80:81], v[176:177]
	ds_read_b128 v[208:211], v2 offset:19456
	v_pk_mul_f32 v[168:169], v[72:73], v[48:49]
	v_pk_mul_f32 v[170:171], v[80:81], v[48:49]
	ds_read_b128 v[212:215], v2 offset:19472
	v_pk_fma_f32 v[164:165], v[74:75], v[178:179], v[164:165]
	v_pk_fma_f32 v[166:167], v[82:83], v[178:179], v[166:167]
	ds_read_b128 v[4:7], v2 offset:7424
	v_pk_fma_f32 v[168:169], v[74:75], v[50:51], v[168:169]
	v_pk_fma_f32 v[170:171], v[82:83], v[50:51], v[170:171]
	ds_read_b128 v[8:11], v2 offset:7440
	s_waitcnt lgkmcnt(12)
	v_pk_fma_f32 v[164:165], v[76:77], v[180:181], v[164:165]
	v_pk_fma_f32 v[166:167], v[84:85], v[180:181], v[166:167]
	ds_read_b128 v[40:43], v2 offset:15616
	v_pk_fma_f32 v[168:169], v[76:77], v[52:53], v[168:169]
	v_pk_fma_f32 v[170:171], v[84:85], v[52:53], v[170:171]
	ds_read_b128 v[44:47], v2 offset:15632
	v_pk_fma_f32 v[164:165], v[78:79], v[182:183], v[164:165]
	v_pk_fma_f32 v[166:167], v[86:87], v[182:183], v[166:167]
	ds_read_b64 v[26:27], v3 offset:44288
	v_pk_fma_f32 v[168:169], v[78:79], v[54:55], v[168:169]
	v_pk_fma_f32 v[170:171], v[86:87], v[54:55], v[170:171]
	ds_read_b128 v[12:15], v2 offset:3328
	s_waitcnt lgkmcnt(13)
	v_pk_mul_f32 v[218:219], v[216:217], v[200:201] op_sel_hi:[0,1]
	v_pk_mul_f32 v[226:227], v[216:217], v[200:201] op_sel:[1,0]
	ds_read_b128 v[28:31], v2 offset:3344
	v_pk_mul_f32 v[220:221], v[216:217], v[202:203] op_sel_hi:[0,1]
	v_pk_mul_f32 v[228:229], v[216:217], v[202:203] op_sel:[1,0]
	ds_read_b128 v[32:35], v2 offset:11520
	v_pk_mul_f32 v[222:223], v[216:217], v[204:205] op_sel_hi:[0,1]
	v_pk_mul_f32 v[230:231], v[216:217], v[204:205] op_sel:[1,0]
	ds_read_b128 v[36:39], v2 offset:11536
	v_pk_mul_f32 v[224:225], v[216:217], v[206:207] op_sel_hi:[0,1]
	v_pk_mul_f32 v[234:235], v[216:217], v[206:207] op_sel:[1,0]
	v_add_f32_e32 v172, v164, v165
	v_add_f32_e32 v174, v166, v167
	v_add_f32_e32 v160, v168, v169
	v_add_f32_e32 v161, v170, v171
	s_waitcnt lgkmcnt(15)
	v_pk_fma_f32 v[218:219], v[72:73], v[184:185], v[218:219]
	v_pk_fma_f32 v[226:227], v[80:81], v[184:185], v[226:227]
	v_pk_fma_f32 v[220:221], v[74:75], v[186:187], v[220:221]
	v_pk_fma_f32 v[228:229], v[82:83], v[186:187], v[228:229]
	v_add_f32_dpp v172, v172, v172 quad_perm:[1,0,3,2] row_mask:0xf bank_mask:0xf bound_ctrl:1
	v_add_f32_dpp v174, v174, v174 quad_perm:[1,0,3,2] row_mask:0xf bank_mask:0xf bound_ctrl:1
	v_add_f32_dpp v160, v160, v160 quad_perm:[1,0,3,2] row_mask:0xf bank_mask:0xf bound_ctrl:1
	v_add_f32_dpp v161, v161, v161 quad_perm:[1,0,3,2] row_mask:0xf bank_mask:0xf bound_ctrl:1
	s_waitcnt lgkmcnt(14)
	v_pk_fma_f32 v[222:223], v[76:77], v[188:189], v[222:223]
	v_pk_fma_f32 v[230:231], v[84:85], v[188:189], v[230:231]
	v_pk_fma_f32 v[224:225], v[78:79], v[190:191], v[224:225]
	v_pk_fma_f32 v[234:235], v[86:87], v[190:191], v[234:235]
	v_add_f32_dpp v172, v172, v172 quad_perm:[2,3,0,1] row_mask:0xf bank_mask:0xf bound_ctrl:1
	v_add_f32_dpp v174, v174, v174 quad_perm:[2,3,0,1] row_mask:0xf bank_mask:0xf bound_ctrl:1
	v_add_f32_dpp v160, v160, v160 quad_perm:[2,3,0,1] row_mask:0xf bank_mask:0xf bound_ctrl:1
	v_add_f32_dpp v161, v161, v161 quad_perm:[2,3,0,1] row_mask:0xf bank_mask:0xf bound_ctrl:1
	v_add_f32_dpp v172, v172, v172 row_half_mirror row_mask:0xf bank_mask:0xf bound_ctrl:1
	v_add_f32_dpp v174, v174, v174 row_half_mirror row_mask:0xf bank_mask:0xf bound_ctrl:1
	v_add_f32_dpp v160, v160, v160 row_half_mirror row_mask:0xf bank_mask:0xf bound_ctrl:1
	v_add_f32_dpp v161, v161, v161 row_half_mirror row_mask:0xf bank_mask:0xf bound_ctrl:1
	s_waitcnt lgkmcnt(13)
	v_pk_fma_f32 v[72:73], v[192:193], v[172:173], v[218:219] op_sel_hi:[1,0,1]
	v_pk_fma_f32 v[80:81], v[192:193], v[174:175], v[226:227] op_sel_hi:[1,0,1]
	v_pk_fma_f32 v[74:75], v[194:195], v[172:173], v[220:221] op_sel_hi:[1,0,1]
	v_pk_fma_f32 v[82:83], v[194:195], v[174:175], v[228:229] op_sel_hi:[1,0,1]
	s_waitcnt lgkmcnt(12)
	v_pk_fma_f32 v[76:77], v[196:197], v[172:173], v[222:223] op_sel_hi:[1,0,1]
	v_pk_fma_f32 v[84:85], v[196:197], v[174:175], v[230:231] op_sel_hi:[1,0,1]
	v_pk_fma_f32 v[78:79], v[198:199], v[172:173], v[224:225] op_sel_hi:[1,0,1]
	v_pk_fma_f32 v[86:87], v[198:199], v[174:175], v[234:235] op_sel_hi:[1,0,1]
	ds_write_b64 v1, v[160:161] offset:56832
	s_waitcnt lgkmcnt(9)
	v_pk_mul_f32 v[164:165], v[72:73], v[4:5]
	v_pk_mul_f32 v[166:167], v[80:81], v[4:5]
	ds_read_b128 v[48:51], v2 offset:19712
	v_pk_mul_f32 v[168:169], v[72:73], v[208:209]
	v_pk_mul_f32 v[170:171], v[80:81], v[208:209]
	ds_read_b128 v[52:55], v2 offset:19728
	v_pk_fma_f32 v[164:165], v[74:75], v[6:7], v[164:165]
	v_pk_fma_f32 v[166:167], v[82:83], v[6:7], v[166:167]
	ds_read_b128 v[176:179], v2 offset:7680
	v_pk_fma_f32 v[168:169], v[74:75], v[210:211], v[168:169]
	v_pk_fma_f32 v[170:171], v[82:83], v[210:211], v[170:171]
	ds_read_b128 v[180:183], v2 offset:7696
	s_waitcnt lgkmcnt(12)
	v_pk_fma_f32 v[164:165], v[76:77], v[8:9], v[164:165]
	v_pk_fma_f32 v[166:167], v[84:85], v[8:9], v[166:167]
	ds_read_b128 v[200:203], v2 offset:15872
	v_pk_fma_f32 v[168:169], v[76:77], v[212:213], v[168:169]
	v_pk_fma_f32 v[170:171], v[84:85], v[212:213], v[170:171]
	ds_read_b128 v[204:207], v2 offset:15888
	v_pk_fma_f32 v[164:165], v[78:79], v[10:11], v[164:165]
	v_pk_fma_f32 v[166:167], v[86:87], v[10:11], v[166:167]
	ds_read_b64 v[216:217], v3 offset:44544
	v_pk_fma_f32 v[168:169], v[78:79], v[214:215], v[168:169]
	v_pk_fma_f32 v[170:171], v[86:87], v[214:215], v[170:171]
	ds_read_b128 v[184:187], v2 offset:3584
	s_waitcnt lgkmcnt(13)
	v_pk_mul_f32 v[218:219], v[26:27], v[40:41] op_sel_hi:[0,1]
	v_pk_mul_f32 v[226:227], v[26:27], v[40:41] op_sel:[1,0]
	ds_read_b128 v[188:191], v2 offset:3600
	v_pk_mul_f32 v[220:221], v[26:27], v[42:43] op_sel_hi:[0,1]
	v_pk_mul_f32 v[228:229], v[26:27], v[42:43] op_sel:[1,0]
	ds_read_b128 v[192:195], v2 offset:11776
	v_pk_mul_f32 v[222:223], v[26:27], v[44:45] op_sel_hi:[0,1]
	v_pk_mul_f32 v[230:231], v[26:27], v[44:45] op_sel:[1,0]
	ds_read_b128 v[196:199], v2 offset:11792
	v_pk_mul_f32 v[224:225], v[26:27], v[46:47] op_sel_hi:[0,1]
	v_pk_mul_f32 v[234:235], v[26:27], v[46:47] op_sel:[1,0]
	v_add_f32_e32 v172, v164, v165
	v_add_f32_e32 v174, v166, v167
	v_add_f32_e32 v160, v168, v169
	v_add_f32_e32 v161, v170, v171
	s_waitcnt lgkmcnt(15)
	v_pk_fma_f32 v[218:219], v[72:73], v[12:13], v[218:219]
	v_pk_fma_f32 v[226:227], v[80:81], v[12:13], v[226:227]
	v_pk_fma_f32 v[220:221], v[74:75], v[14:15], v[220:221]
	v_pk_fma_f32 v[228:229], v[82:83], v[14:15], v[228:229]
	v_add_f32_dpp v172, v172, v172 quad_perm:[1,0,3,2] row_mask:0xf bank_mask:0xf bound_ctrl:1
	v_add_f32_dpp v174, v174, v174 quad_perm:[1,0,3,2] row_mask:0xf bank_mask:0xf bound_ctrl:1
	v_add_f32_dpp v160, v160, v160 quad_perm:[1,0,3,2] row_mask:0xf bank_mask:0xf bound_ctrl:1
	v_add_f32_dpp v161, v161, v161 quad_perm:[1,0,3,2] row_mask:0xf bank_mask:0xf bound_ctrl:1
	s_waitcnt lgkmcnt(14)
	v_pk_fma_f32 v[222:223], v[76:77], v[28:29], v[222:223]
	v_pk_fma_f32 v[230:231], v[84:85], v[28:29], v[230:231]
	v_pk_fma_f32 v[224:225], v[78:79], v[30:31], v[224:225]
	v_pk_fma_f32 v[234:235], v[86:87], v[30:31], v[234:235]
	v_add_f32_dpp v172, v172, v172 quad_perm:[2,3,0,1] row_mask:0xf bank_mask:0xf bound_ctrl:1
	v_add_f32_dpp v174, v174, v174 quad_perm:[2,3,0,1] row_mask:0xf bank_mask:0xf bound_ctrl:1
	v_add_f32_dpp v160, v160, v160 quad_perm:[2,3,0,1] row_mask:0xf bank_mask:0xf bound_ctrl:1
	v_add_f32_dpp v161, v161, v161 quad_perm:[2,3,0,1] row_mask:0xf bank_mask:0xf bound_ctrl:1
	v_add_f32_dpp v172, v172, v172 row_half_mirror row_mask:0xf bank_mask:0xf bound_ctrl:1
	v_add_f32_dpp v174, v174, v174 row_half_mirror row_mask:0xf bank_mask:0xf bound_ctrl:1
	v_add_f32_dpp v160, v160, v160 row_half_mirror row_mask:0xf bank_mask:0xf bound_ctrl:1
	v_add_f32_dpp v161, v161, v161 row_half_mirror row_mask:0xf bank_mask:0xf bound_ctrl:1
	s_waitcnt lgkmcnt(13)
	v_pk_fma_f32 v[72:73], v[32:33], v[172:173], v[218:219] op_sel_hi:[1,0,1]
	v_pk_fma_f32 v[80:81], v[32:33], v[174:175], v[226:227] op_sel_hi:[1,0,1]
	v_pk_fma_f32 v[74:75], v[34:35], v[172:173], v[220:221] op_sel_hi:[1,0,1]
	v_pk_fma_f32 v[82:83], v[34:35], v[174:175], v[228:229] op_sel_hi:[1,0,1]
	s_waitcnt lgkmcnt(12)
	v_pk_fma_f32 v[76:77], v[36:37], v[172:173], v[222:223] op_sel_hi:[1,0,1]
	v_pk_fma_f32 v[84:85], v[36:37], v[174:175], v[230:231] op_sel_hi:[1,0,1]
	v_pk_fma_f32 v[78:79], v[38:39], v[172:173], v[224:225] op_sel_hi:[1,0,1]
	v_pk_fma_f32 v[86:87], v[38:39], v[174:175], v[234:235] op_sel_hi:[1,0,1]
	ds_write_b64 v1, v[160:161] offset:57088
	s_waitcnt lgkmcnt(9)
	v_pk_mul_f32 v[164:165], v[72:73], v[176:177]
	v_pk_mul_f32 v[166:167], v[80:81], v[176:177]
	ds_read_b128 v[208:211], v2 offset:19968
	v_pk_mul_f32 v[168:169], v[72:73], v[48:49]
	v_pk_mul_f32 v[170:171], v[80:81], v[48:49]
	ds_read_b128 v[212:215], v2 offset:19984
	v_pk_fma_f32 v[164:165], v[74:75], v[178:179], v[164:165]
	v_pk_fma_f32 v[166:167], v[82:83], v[178:179], v[166:167]
	ds_read_b128 v[4:7], v2 offset:7936
	v_pk_fma_f32 v[168:169], v[74:75], v[50:51], v[168:169]
	v_pk_fma_f32 v[170:171], v[82:83], v[50:51], v[170:171]
	ds_read_b128 v[8:11], v2 offset:7952
	s_waitcnt lgkmcnt(12)
	v_pk_fma_f32 v[164:165], v[76:77], v[180:181], v[164:165]
	v_pk_fma_f32 v[166:167], v[84:85], v[180:181], v[166:167]
	ds_read_b128 v[40:43], v2 offset:16128
	v_pk_fma_f32 v[168:169], v[76:77], v[52:53], v[168:169]
	v_pk_fma_f32 v[170:171], v[84:85], v[52:53], v[170:171]
	ds_read_b128 v[44:47], v2 offset:16144
	v_pk_fma_f32 v[164:165], v[78:79], v[182:183], v[164:165]
	v_pk_fma_f32 v[166:167], v[86:87], v[182:183], v[166:167]
	ds_read_b64 v[26:27], v3 offset:44800
	v_pk_fma_f32 v[168:169], v[78:79], v[54:55], v[168:169]
	v_pk_fma_f32 v[170:171], v[86:87], v[54:55], v[170:171]
	ds_read_b128 v[12:15], v2 offset:3840
	s_waitcnt lgkmcnt(13)
	v_pk_mul_f32 v[218:219], v[216:217], v[200:201] op_sel_hi:[0,1]
	v_pk_mul_f32 v[226:227], v[216:217], v[200:201] op_sel:[1,0]
	ds_read_b128 v[28:31], v2 offset:3856
	v_pk_mul_f32 v[220:221], v[216:217], v[202:203] op_sel_hi:[0,1]
	v_pk_mul_f32 v[228:229], v[216:217], v[202:203] op_sel:[1,0]
	ds_read_b128 v[32:35], v2 offset:12032
	v_pk_mul_f32 v[222:223], v[216:217], v[204:205] op_sel_hi:[0,1]
	v_pk_mul_f32 v[230:231], v[216:217], v[204:205] op_sel:[1,0]
	ds_read_b128 v[36:39], v2 offset:12048
	v_pk_mul_f32 v[224:225], v[216:217], v[206:207] op_sel_hi:[0,1]
	v_pk_mul_f32 v[234:235], v[216:217], v[206:207] op_sel:[1,0]
	v_add_f32_e32 v172, v164, v165
	v_add_f32_e32 v174, v166, v167
	v_add_f32_e32 v160, v168, v169
	v_add_f32_e32 v161, v170, v171
	s_waitcnt lgkmcnt(15)
	v_pk_fma_f32 v[218:219], v[72:73], v[184:185], v[218:219]
	v_pk_fma_f32 v[226:227], v[80:81], v[184:185], v[226:227]
	v_pk_fma_f32 v[220:221], v[74:75], v[186:187], v[220:221]
	v_pk_fma_f32 v[228:229], v[82:83], v[186:187], v[228:229]
	v_add_f32_dpp v172, v172, v172 quad_perm:[1,0,3,2] row_mask:0xf bank_mask:0xf bound_ctrl:1
	v_add_f32_dpp v174, v174, v174 quad_perm:[1,0,3,2] row_mask:0xf bank_mask:0xf bound_ctrl:1
	v_add_f32_dpp v160, v160, v160 quad_perm:[1,0,3,2] row_mask:0xf bank_mask:0xf bound_ctrl:1
	v_add_f32_dpp v161, v161, v161 quad_perm:[1,0,3,2] row_mask:0xf bank_mask:0xf bound_ctrl:1
	s_waitcnt lgkmcnt(14)
	v_pk_fma_f32 v[222:223], v[76:77], v[188:189], v[222:223]
	v_pk_fma_f32 v[230:231], v[84:85], v[188:189], v[230:231]
	v_pk_fma_f32 v[224:225], v[78:79], v[190:191], v[224:225]
	v_pk_fma_f32 v[234:235], v[86:87], v[190:191], v[234:235]
	v_add_f32_dpp v172, v172, v172 quad_perm:[2,3,0,1] row_mask:0xf bank_mask:0xf bound_ctrl:1
	v_add_f32_dpp v174, v174, v174 quad_perm:[2,3,0,1] row_mask:0xf bank_mask:0xf bound_ctrl:1
	v_add_f32_dpp v160, v160, v160 quad_perm:[2,3,0,1] row_mask:0xf bank_mask:0xf bound_ctrl:1
	v_add_f32_dpp v161, v161, v161 quad_perm:[2,3,0,1] row_mask:0xf bank_mask:0xf bound_ctrl:1
	v_add_f32_dpp v172, v172, v172 row_half_mirror row_mask:0xf bank_mask:0xf bound_ctrl:1
	v_add_f32_dpp v174, v174, v174 row_half_mirror row_mask:0xf bank_mask:0xf bound_ctrl:1
	v_add_f32_dpp v160, v160, v160 row_half_mirror row_mask:0xf bank_mask:0xf bound_ctrl:1
	v_add_f32_dpp v161, v161, v161 row_half_mirror row_mask:0xf bank_mask:0xf bound_ctrl:1
	s_waitcnt lgkmcnt(13)
	v_pk_fma_f32 v[72:73], v[192:193], v[172:173], v[218:219] op_sel_hi:[1,0,1]
	v_pk_fma_f32 v[80:81], v[192:193], v[174:175], v[226:227] op_sel_hi:[1,0,1]
	v_pk_fma_f32 v[74:75], v[194:195], v[172:173], v[220:221] op_sel_hi:[1,0,1]
	v_pk_fma_f32 v[82:83], v[194:195], v[174:175], v[228:229] op_sel_hi:[1,0,1]
	s_waitcnt lgkmcnt(12)
	v_pk_fma_f32 v[76:77], v[196:197], v[172:173], v[222:223] op_sel_hi:[1,0,1]
	v_pk_fma_f32 v[84:85], v[196:197], v[174:175], v[230:231] op_sel_hi:[1,0,1]
	v_pk_fma_f32 v[78:79], v[198:199], v[172:173], v[224:225] op_sel_hi:[1,0,1]
	v_pk_fma_f32 v[86:87], v[198:199], v[174:175], v[234:235] op_sel_hi:[1,0,1]
	ds_write_b64 v1, v[160:161] offset:57344
	s_waitcnt lgkmcnt(9)
	v_pk_mul_f32 v[164:165], v[72:73], v[4:5]
	v_pk_mul_f32 v[166:167], v[80:81], v[4:5]
	ds_read_b128 v[48:51], v2 offset:20224
	v_pk_mul_f32 v[168:169], v[72:73], v[208:209]
	v_pk_mul_f32 v[170:171], v[80:81], v[208:209]
	ds_read_b128 v[52:55], v2 offset:20240
	v_pk_fma_f32 v[164:165], v[74:75], v[6:7], v[164:165]
	v_pk_fma_f32 v[166:167], v[82:83], v[6:7], v[166:167]
	v_pk_fma_f32 v[168:169], v[74:75], v[210:211], v[168:169]
	v_pk_fma_f32 v[170:171], v[82:83], v[210:211], v[170:171]
	s_waitcnt lgkmcnt(10)
	v_pk_fma_f32 v[164:165], v[76:77], v[8:9], v[164:165]
	v_pk_fma_f32 v[166:167], v[84:85], v[8:9], v[166:167]
	v_pk_fma_f32 v[168:169], v[76:77], v[212:213], v[168:169]
	v_pk_fma_f32 v[170:171], v[84:85], v[212:213], v[170:171]
	v_pk_fma_f32 v[164:165], v[78:79], v[10:11], v[164:165]
	v_pk_fma_f32 v[166:167], v[86:87], v[10:11], v[166:167]
	v_pk_fma_f32 v[168:169], v[78:79], v[214:215], v[168:169]
	v_pk_fma_f32 v[170:171], v[86:87], v[214:215], v[170:171]
	s_waitcnt lgkmcnt(7)
	v_pk_mul_f32 v[218:219], v[26:27], v[40:41] op_sel_hi:[0,1]
	v_pk_mul_f32 v[226:227], v[26:27], v[40:41] op_sel:[1,0]
	v_pk_mul_f32 v[220:221], v[26:27], v[42:43] op_sel_hi:[0,1]
	v_pk_mul_f32 v[228:229], v[26:27], v[42:43] op_sel:[1,0]
	v_pk_mul_f32 v[222:223], v[26:27], v[44:45] op_sel_hi:[0,1]
	v_pk_mul_f32 v[230:231], v[26:27], v[44:45] op_sel:[1,0]
	v_pk_mul_f32 v[224:225], v[26:27], v[46:47] op_sel_hi:[0,1]
	v_pk_mul_f32 v[234:235], v[26:27], v[46:47] op_sel:[1,0]
	v_add_f32_e32 v172, v164, v165
	v_add_f32_e32 v174, v166, v167
	v_add_f32_e32 v160, v168, v169
	v_add_f32_e32 v161, v170, v171
	s_waitcnt lgkmcnt(6)
	v_pk_fma_f32 v[218:219], v[72:73], v[12:13], v[218:219]
	v_pk_fma_f32 v[226:227], v[80:81], v[12:13], v[226:227]
	v_pk_fma_f32 v[220:221], v[74:75], v[14:15], v[220:221]
	v_pk_fma_f32 v[228:229], v[82:83], v[14:15], v[228:229]
	v_add_f32_dpp v172, v172, v172 quad_perm:[1,0,3,2] row_mask:0xf bank_mask:0xf bound_ctrl:1
	v_add_f32_dpp v174, v174, v174 quad_perm:[1,0,3,2] row_mask:0xf bank_mask:0xf bound_ctrl:1
	v_add_f32_dpp v160, v160, v160 quad_perm:[1,0,3,2] row_mask:0xf bank_mask:0xf bound_ctrl:1
	v_add_f32_dpp v161, v161, v161 quad_perm:[1,0,3,2] row_mask:0xf bank_mask:0xf bound_ctrl:1
	s_waitcnt lgkmcnt(5)
	v_pk_fma_f32 v[222:223], v[76:77], v[28:29], v[222:223]
	v_pk_fma_f32 v[230:231], v[84:85], v[28:29], v[230:231]
	v_pk_fma_f32 v[224:225], v[78:79], v[30:31], v[224:225]
	v_pk_fma_f32 v[234:235], v[86:87], v[30:31], v[234:235]
	v_add_f32_dpp v172, v172, v172 quad_perm:[2,3,0,1] row_mask:0xf bank_mask:0xf bound_ctrl:1
	v_add_f32_dpp v174, v174, v174 quad_perm:[2,3,0,1] row_mask:0xf bank_mask:0xf bound_ctrl:1
	v_add_f32_dpp v160, v160, v160 quad_perm:[2,3,0,1] row_mask:0xf bank_mask:0xf bound_ctrl:1
	v_add_f32_dpp v161, v161, v161 quad_perm:[2,3,0,1] row_mask:0xf bank_mask:0xf bound_ctrl:1
	v_add_f32_dpp v172, v172, v172 row_half_mirror row_mask:0xf bank_mask:0xf bound_ctrl:1
	v_add_f32_dpp v174, v174, v174 row_half_mirror row_mask:0xf bank_mask:0xf bound_ctrl:1
	v_add_f32_dpp v160, v160, v160 row_half_mirror row_mask:0xf bank_mask:0xf bound_ctrl:1
	v_add_f32_dpp v161, v161, v161 row_half_mirror row_mask:0xf bank_mask:0xf bound_ctrl:1
	s_waitcnt lgkmcnt(4)
	v_pk_fma_f32 v[72:73], v[32:33], v[172:173], v[218:219] op_sel_hi:[1,0,1]
	v_pk_fma_f32 v[80:81], v[32:33], v[174:175], v[226:227] op_sel_hi:[1,0,1]
	v_pk_fma_f32 v[74:75], v[34:35], v[172:173], v[220:221] op_sel_hi:[1,0,1]
	v_pk_fma_f32 v[82:83], v[34:35], v[174:175], v[228:229] op_sel_hi:[1,0,1]
	s_waitcnt lgkmcnt(3)
	v_pk_fma_f32 v[76:77], v[36:37], v[172:173], v[222:223] op_sel_hi:[1,0,1]
	v_pk_fma_f32 v[84:85], v[36:37], v[174:175], v[230:231] op_sel_hi:[1,0,1]
	v_pk_fma_f32 v[78:79], v[38:39], v[172:173], v[224:225] op_sel_hi:[1,0,1]
	v_pk_fma_f32 v[86:87], v[38:39], v[174:175], v[234:235] op_sel_hi:[1,0,1]
	ds_write_b64 v1, v[160:161] offset:57600
	s_waitcnt lgkmcnt(2)
	v_pk_mul_f32 v[168:169], v[72:73], v[48:49]
	v_pk_mul_f32 v[170:171], v[80:81], v[48:49]
	v_pk_fma_f32 v[168:169], v[74:75], v[50:51], v[168:169]
	v_pk_fma_f32 v[170:171], v[82:83], v[50:51], v[170:171]
	s_waitcnt lgkmcnt(1)
	v_pk_fma_f32 v[168:169], v[76:77], v[52:53], v[168:169]
	v_pk_fma_f32 v[170:171], v[84:85], v[52:53], v[170:171]
	v_pk_fma_f32 v[168:169], v[78:79], v[54:55], v[168:169]
	v_pk_fma_f32 v[170:171], v[86:87], v[54:55], v[170:171]
	v_add_f32_e32 v160, v168, v169
	v_add_f32_e32 v161, v170, v171
	s_nop 0
	v_add_f32_dpp v160, v160, v160 quad_perm:[1,0,3,2] row_mask:0xf bank_mask:0xf bound_ctrl:1
	v_add_f32_dpp v161, v161, v161 quad_perm:[1,0,3,2] row_mask:0xf bank_mask:0xf bound_ctrl:1
	s_nop 0
	v_add_f32_dpp v160, v160, v160 quad_perm:[2,3,0,1] row_mask:0xf bank_mask:0xf bound_ctrl:1
	v_add_f32_dpp v161, v161, v161 quad_perm:[2,3,0,1] row_mask:0xf bank_mask:0xf bound_ctrl:1
	s_nop 0
	v_add_f32_dpp v160, v160, v160 row_half_mirror row_mask:0xf bank_mask:0xf bound_ctrl:1
	v_add_f32_dpp v161, v161, v161 row_half_mirror row_mask:0xf bank_mask:0xf bound_ctrl:1
	ds_write_b64 v1, v[160:161] offset:57856
	s_add_i32 s3, s2, 1
	s_mov_b64 s[36:37], 0
